# E28: E27 + mixer tiles drop two self-max canonicalisations after permlane swap and start row-sum chains at p0+p1 (no 0+p0), cold pad keeps later code phase
# baseline (speedup 1.0000x reference)
; template <class MB> __device__ __forceinline__ void la_soft(LA& st, f32x16& s, const TP& t, bf16x8& pf0, bf16x8& pf1) {
;     float mx = NEGBIG;
; #pragma unroll
;     for (int r = 0; r < 16; ++r) { s[r] = MB::apply(t, r, s[r]); mx = __builtin_fmaxf(mx, s[r]); }
;     { auto rr = __builtin_amdgcn_permlane32_swap(__float_as_uint(mx), __float_as_uint(mx), false, false); mx = __builtin_fmaxf(__uint_as_float(rr[0]), __uint_as_float(rr[1])); }
;     if (__any(mx > st.m)) { const float mn = __builtin_fmaxf(st.m, mx), alpha = __builtin_amdgcn_exp2f(st.m - mn); st.m = mn; st.l *= alpha; st.o0 *= alpha; st.o1 *= alpha; }
; template <class MB, int V1, class VS> __device__ __forceinline__ void la_step2(LA& sa, LA& sb, const bf16x8 (&qa)[4], const bf16x8 (&qb)[4], Frag& f, const char* kb, const VS& vs, const TP& t, const TP& n) {
;     bf16x8 pa0, pa1;
;     { f32x16 s0 = zero16();
; #pragma unroll
;       for (int d0 = 0; d0 < 4; ++d0) s0 = __builtin_amdgcn_mfma_f32_32x32x16_bf16(f.k[d0], qa[d0], s0, 0, 0, 0);
;       la_soft<MB>(sa, s0, t, pa0, pa1); }
;     f32x16 s1 = zero16();
; #pragma unroll
;     for (int d0 = 0; d0 < 4; ++d0) s1 = __builtin_amdgcn_mfma_f32_32x32x16_bf16(f.k[d0], qb[d0], s1, 0, 0, 0);
;     la_loadK(f, kb, n);
;     sa.o0 = __builtin_amdgcn_mfma_f32_32x32x16_bf16(f.v[0], pa0, sa.o0, 0, 0, 0); sa.o1 = __builtin_amdgcn_mfma_f32_32x32x16_bf16(f.v[2], pa0, sa.o1, 0, 0, 0);
;     sa.o0 = __builtin_amdgcn_mfma_f32_32x32x16_bf16(f.v[1], pa1, sa.o0, 0, 0, 0); sa.o1 = __builtin_amdgcn_mfma_f32_32x32x16_bf16(f.v[3], pa1, sa.o1, 0, 0, 0);
;     { bf16x8 pb0, pb1; const TP tb = MB::second(t);
;       la_soft<MB>(sb, s1, tb, pb0, pb1);
;       sb.o0 = __builtin_amdgcn_mfma_f32_32x32x16_bf16(f.v[0], pb0, sb.o0, 0, 0, 0); sb.o1 = __builtin_amdgcn_mfma_f32_32x32x16_bf16(f.v[2], pb0, sb.o1, 0, 0, 0);
;       sb.o0 = __builtin_amdgcn_mfma_f32_32x32x16_bf16(f.v[1], pb1, sb.o0, 0, 0, 0); sb.o1 = __builtin_amdgcn_mfma_f32_32x32x16_bf16(f.v[3], pb1, sb.o1, 0, 0, 0); }
.LBB0_661:
	s_add_i32 s4, s7, s9
	s_addk_i32 s4, 0xffa0
	s_cmpk_lt_u32 s4, 0x4000
	v_lshl_add_u32 v64, v64, 1, v148
	s_cselect_b64 s[4:5], -1, 0
	s_cmpk_lg_i32 s9, 0xc0
	v_add_u32_e32 v65, 0x9000, v64
	s_cselect_b64 s[10:11], -1, 0
	ds_read_b128 v[136:139], v65 offset:41472
	ds_read_b128 v[128:131], v65 offset:41504
	ds_read_b128 v[140:143], v64 offset:36864
	ds_read_b128 v[132:135], v64 offset:36896
	s_and_b64 vcc, s[10:11], s[4:5]
	v_add_u32_e32 v150, 0x80, v152
	v_mov_b32_e32 v64, s53
	v_cndmask_b32_e32 v167, v64, v150, vcc
	ds_read2_b32 v[154:155], v167 offset1:1
	s_waitcnt vmcnt(3)
	s_nop 0
	v_mfma_f32_32x32x16_bf16 v[64:79], v[124:127], v[96:99], 0
	s_waitcnt vmcnt(2)
	v_mfma_f32_32x32x16_bf16 v[64:79], v[120:123], v[88:91], v[64:79]
	s_waitcnt vmcnt(1)
	v_mfma_f32_32x32x16_bf16 v[64:79], v[116:119], v[92:95], v[64:79]
	s_waitcnt vmcnt(0)
	v_mfma_f32_32x32x16_bf16 v[64:79], v[112:115], v[100:103], v[64:79]
	s_waitcnt lgkmcnt(0)
	s_nop 10
	v_add_f32_e32 v154, v64, v154
	v_add_f32_e32 v153, v65, v155
	ds_read2_b32 v[64:65], v167 offset0:2 offset1:3
	v_max3_f32 v157, v154, s2, v153
	s_waitcnt lgkmcnt(0)
	v_add_f32_e32 v156, v66, v64
	v_add_f32_e32 v155, v67, v65
	ds_read2_b32 v[64:65], v167 offset0:4 offset1:5
	v_max3_f32 v66, v157, v156, v155
	s_waitcnt lgkmcnt(0)
	v_add_f32_e32 v158, v68, v64
	v_add_f32_e32 v157, v69, v65
	ds_read2_b32 v[64:65], v167 offset0:6 offset1:7
	v_max3_f32 v66, v66, v158, v157
	s_waitcnt lgkmcnt(0)
	v_add_f32_e32 v160, v70, v64
	v_add_f32_e32 v159, v71, v65
	ds_read2_b32 v[64:65], v167 offset0:16 offset1:17
	v_max3_f32 v66, v66, v160, v159
	s_waitcnt lgkmcnt(0)
	v_add_f32_e32 v162, v72, v64
	v_add_f32_e32 v161, v73, v65
	ds_read2_b32 v[64:65], v167 offset0:18 offset1:19
	v_max3_f32 v66, v66, v162, v161
	s_waitcnt lgkmcnt(0)
	v_add_f32_e32 v166, v74, v64
	v_add_f32_e32 v165, v75, v65
	ds_read2_b32 v[64:65], v167 offset0:20 offset1:21
	v_max3_f32 v66, v66, v166, v165
	s_waitcnt lgkmcnt(0)
	v_add_f32_e32 v164, v76, v64
	v_add_f32_e32 v163, v77, v65
	ds_read2_b32 v[64:65], v167 offset0:22 offset1:23
	v_max3_f32 v66, v66, v164, v163
	s_waitcnt lgkmcnt(0)
	v_add_f32_e32 v168, v78, v64
	v_add_f32_e32 v167, v79, v65
	v_max3_f32 v64, v66, v168, v167
	v_mov_b32_e32 v65, v64
	s_nop 1
	v_permlane32_swap_b32_e32 v64, v65
	v_max_f32_e32 v64, v64, v65
	v_cmp_gt_f32_e32 vcc, v64, v151
	s_cbranch_vccz .LBB0_663
	v_max_f32_e32 v64, v64, v64
	v_max_f32_e32 v65, v151, v151
	v_max_f32_e32 v65, v65, v64
	v_sub_f32_e32 v64, v151, v65
	v_exp_f32_e32 v64, v64
	v_mov_b32_e32 v151, v65
	v_mul_f32_e32 v147, v64, v147
	v_pk_mul_f32 v[46:47], v[64:65], v[46:47] op_sel_hi:[0,1]
	v_pk_mul_f32 v[44:45], v[64:65], v[44:45] op_sel_hi:[0,1]
	v_pk_mul_f32 v[42:43], v[64:65], v[42:43] op_sel_hi:[0,1]
	v_pk_mul_f32 v[40:41], v[64:65], v[40:41] op_sel_hi:[0,1]
	v_pk_mul_f32 v[38:39], v[64:65], v[38:39] op_sel_hi:[0,1]
	v_pk_mul_f32 v[36:37], v[64:65], v[36:37] op_sel_hi:[0,1]
	v_pk_mul_f32 v[34:35], v[64:65], v[34:35] op_sel_hi:[0,1]
	v_pk_mul_f32 v[32:33], v[64:65], v[32:33] op_sel_hi:[0,1]
	v_pk_mul_f32 v[62:63], v[64:65], v[62:63] op_sel_hi:[0,1]
	v_pk_mul_f32 v[60:61], v[64:65], v[60:61] op_sel_hi:[0,1]
	v_pk_mul_f32 v[58:59], v[64:65], v[58:59] op_sel_hi:[0,1]
	v_pk_mul_f32 v[56:57], v[64:65], v[56:57] op_sel_hi:[0,1]
	v_pk_mul_f32 v[54:55], v[64:65], v[54:55] op_sel_hi:[0,1]
	v_pk_mul_f32 v[52:53], v[64:65], v[52:53] op_sel_hi:[0,1]
	v_pk_mul_f32 v[50:51], v[64:65], v[50:51] op_sel_hi:[0,1]
	v_pk_mul_f32 v[48:49], v[64:65], v[48:49] op_sel_hi:[0,1]
.LBB0_663:
	s_cmp_lg_u32 s9, 32
	s_cselect_b64 s[10:11], -1, 0
	s_and_b64 vcc, s[10:11], s[4:5]
	s_cmpk_lg_i32 s9, 0xc0
	s_cselect_b32 s4, s9, 0xa0
	s_add_i32 s5, s8, s4
	s_cmpk_lt_u32 s5, 0x4000
	s_cselect_b32 s5, s5, s7
	v_or_b32_e32 v64, s5, v185
	v_mul_lo_u32 v64, v64, s67
	v_add_lshl_u32 v175, v64, v181, 1
	v_mov_b32_e32 v174, s53
	v_cndmask_b32_e32 v180, v174, v152, vcc
	s_nop 0
	v_mfma_f32_32x32x16_bf16 v[64:79], v[124:127], v[80:83], 0
	v_sub_f32_e32 v124, v154, v151
	v_exp_f32_e32 v154, v124
	v_sub_f32_e32 v124, v153, v151
	v_exp_f32_e32 v153, v124
	v_sub_f32_e32 v124, v156, v151
	v_exp_f32_e32 v156, v124
	v_sub_f32_e32 v124, v155, v151
	v_mfma_f32_32x32x16_bf16 v[64:79], v[120:123], v[84:87], v[64:79]
	v_sub_f32_e32 v120, v158, v151
	v_exp_f32_e32 v158, v120
	v_sub_f32_e32 v120, v157, v151
	v_exp_f32_e32 v157, v120
	v_sub_f32_e32 v120, v160, v151
	v_exp_f32_e32 v155, v124
	v_exp_f32_e32 v160, v120
	v_mfma_f32_32x32x16_bf16 v[64:79], v[116:119], v[104:107], v[64:79]
	v_sub_f32_e32 v116, v159, v151
	v_exp_f32_e32 v159, v116
	v_sub_f32_e32 v116, v162, v151
	v_exp_f32_e32 v162, v116
	v_sub_f32_e32 v116, v161, v151
	v_exp_f32_e32 v161, v116
	v_sub_f32_e32 v116, v166, v151
	v_exp_f32_e32 v166, v116
	v_sub_f32_e32 v116, v164, v151
	v_exp_f32_e32 v164, v116
	v_sub_f32_e32 v116, v163, v151
	v_mfma_f32_32x32x16_bf16 v[64:79], v[112:115], v[108:111], v[64:79]
	v_sub_f32_e32 v112, v165, v151
	v_exp_f32_e32 v169, v116
	v_sub_f32_e32 v116, v168, v151
	v_exp_f32_e32 v165, v112
	v_cvt_pk_bf16_f32 v112, v154, v153
	v_cvt_pk_bf16_f32 v113, v156, v155
	v_cvt_pk_bf16_f32 v114, v158, v157
	v_cvt_pk_bf16_f32 v115, v160, v159
	v_exp_f32_e32 v168, v116
	v_sub_f32_e32 v116, v167, v151
	v_mfma_f32_32x32x16_bf16 v[32:47], v[140:143], v[112:115], v[32:47]
	v_exp_f32_e32 v163, v116
	global_load_dwordx4 v[124:127], v175, s[74:75]
	global_load_dwordx4 v[120:123], v175, s[74:75] offset:32
	v_cvt_pk_bf16_f32 v170, v162, v161
	v_cvt_pk_bf16_f32 v171, v166, v165
	v_cvt_pk_bf16_f32 v172, v164, v169
	v_cvt_pk_bf16_f32 v173, v168, v163
	v_mfma_f32_32x32x16_bf16 v[48:63], v[136:139], v[112:115], v[48:63]
	global_load_dwordx4 v[116:119], v175, s[74:75] offset:64
	global_load_dwordx4 v[112:115], v175, s[74:75] offset:96
	ds_read2_b32 v[174:175], v180 offset1:1
	ds_read2_b32 v[176:177], v180 offset0:2 offset1:3
	ds_read2_b32 v[178:179], v180 offset0:4 offset1:5
	ds_read2_b32 v[182:183], v180 offset0:6 offset1:7
	s_waitcnt lgkmcnt(3)
; __device__ __forceinline__ unsigned cvt_pk_bf16(float lo, float hi) { f32x2_c v = {lo, hi}; bf16x2_c b = __builtin_convertvector(v, bf16x2_c); return __builtin_bit_cast(unsigned, b); }
; template <class MB> __device__ __forceinline__ void la_soft(LA& st, f32x16& s, const TP& t, bf16x8& pf0, bf16x8& pf1) {
;     ...
;     if (__any(mx > st.m)) { const float mn = __builtin_fmaxf(st.m, mx), alpha = __builtin_amdgcn_exp2f(st.m - mn); st.m = mn; st.l *= alpha; st.o0 *= alpha; st.o1 *= alpha; }
;     float rs = 0.f;
; #pragma unroll
;     for (int r = 0; r < 16; ++r) { s[r] = __builtin_amdgcn_exp2f(s[r] - st.m); rs += s[r]; }
;     st.l += rs;
;     u32x4 p0, p1;
; #pragma unroll
;     for (int e = 0; e < 4; ++e) { p0[e] = cvt_pk_bf16(s[2 * e], s[2 * e + 1]); p1[e] = cvt_pk_bf16(s[8 + 2 * e], s[8 + 2 * e + 1]); }
;     pf0 = __builtin_bit_cast(bf16x8, p0); pf1 = __builtin_bit_cast(bf16x8, p1);
; }
; template <class MB, int V1, class VS> __device__ __forceinline__ void la_step2(LA& sa, LA& sb, const bf16x8 (&qa)[4], const bf16x8 (&qb)[4], Frag& f, const char* kb, const VS& vs, const TP& t, const TP& n) {
;     ...
;     { bf16x8 pb0, pb1; const TP tb = MB::second(t);
;       la_soft<MB>(sb, s1, tb, pb0, pb1);
;       sb.o0 = __builtin_amdgcn_mfma_f32_32x32x16_bf16(f.v[0], pb0, sb.o0, 0, 0, 0); sb.o1 = __builtin_amdgcn_mfma_f32_32x32x16_bf16(f.v[2], pb0, sb.o1, 0, 0, 0);
;       sb.o0 = __builtin_amdgcn_mfma_f32_32x32x16_bf16(f.v[1], pb1, sb.o0, 0, 0, 0); sb.o1 = __builtin_amdgcn_mfma_f32_32x32x16_bf16(f.v[3], pb1, sb.o1, 0, 0, 0); }
	v_add_f32_e32 v174, v64, v174
	v_mfma_f32_32x32x16_bf16 v[32:47], v[132:135], v[170:173], v[32:47]
	s_waitcnt lgkmcnt(1)
	v_add_f32_e32 v167, v68, v178
	v_add_f32_e32 v152, v69, v179
	s_waitcnt lgkmcnt(0)
	v_add_f32_e32 v70, v70, v182
	v_add_f32_e32 v69, v71, v183
	v_mfma_f32_32x32x16_bf16 v[48:63], v[128:131], v[170:173], v[48:63]
	v_add_f32_e32 v173, v65, v175
	v_max3_f32 v64, v174, s2, v173
	v_add_f32_e32 v171, v66, v176
	v_add_f32_e32 v170, v67, v177
	v_max3_f32 v64, v64, v171, v170
	v_max3_f32 v66, v64, v167, v152
	ds_read2_b32 v[64:65], v180 offset0:16 offset1:17
	v_max3_f32 v68, v66, v70, v69
	ds_read2_b32 v[66:67], v180 offset0:18 offset1:19
	ds_read2_b32 v[176:177], v180 offset0:20 offset1:21
	ds_read2_b32 v[178:179], v180 offset0:22 offset1:23
	s_waitcnt lgkmcnt(3)
	v_add_f32_e32 v172, v72, v64
	v_add_f32_e32 v72, v73, v65
	v_max3_f32 v64, v68, v172, v72
	s_waitcnt lgkmcnt(2)
	v_add_f32_e32 v71, v74, v66
	v_add_f32_e32 v67, v75, v67
	v_max3_f32 v64, v64, v71, v67
	s_waitcnt lgkmcnt(1)
	v_add_f32_e32 v68, v76, v176
	v_add_f32_e32 v65, v77, v177
	v_max3_f32 v73, v64, v68, v65
	s_waitcnt lgkmcnt(0)
	v_add_f32_e32 v66, v78, v178
	v_add_f32_e32 v64, v79, v179
	v_max3_f32 v73, v73, v66, v64
	v_mov_b32_e32 v74, v73
	s_nop 1
	v_permlane32_swap_b32_e32 v73, v74
	v_max_f32_e32 v73, v73, v74
	v_cmp_gt_f32_e32 vcc, v73, v145
	s_cbranch_vccz .LBB0_665
	v_max_f32_e32 v73, v73, v73
	v_max_f32_e32 v74, v145, v145
	v_max_f32_e32 v73, v74, v73
	v_sub_f32_e32 v74, v145, v73
	v_exp_f32_e32 v74, v74
	v_mov_b32_e32 v145, v73
	v_mul_f32_e32 v144, v74, v144
	v_pk_mul_f32 v[14:15], v[74:75], v[14:15] op_sel_hi:[0,1]
	v_pk_mul_f32 v[12:13], v[74:75], v[12:13] op_sel_hi:[0,1]
	v_pk_mul_f32 v[10:11], v[74:75], v[10:11] op_sel_hi:[0,1]
	v_pk_mul_f32 v[8:9], v[74:75], v[8:9] op_sel_hi:[0,1]
	v_pk_mul_f32 v[6:7], v[74:75], v[6:7] op_sel_hi:[0,1]
	v_pk_mul_f32 v[4:5], v[74:75], v[4:5] op_sel_hi:[0,1]
	v_pk_mul_f32 v[2:3], v[74:75], v[2:3] op_sel_hi:[0,1]
	v_pk_mul_f32 v[0:1], v[74:75], v[0:1] op_sel_hi:[0,1]
	v_pk_mul_f32 v[30:31], v[74:75], v[30:31] op_sel_hi:[0,1]
	v_pk_mul_f32 v[28:29], v[74:75], v[28:29] op_sel_hi:[0,1]
	v_pk_mul_f32 v[26:27], v[74:75], v[26:27] op_sel_hi:[0,1]
	v_pk_mul_f32 v[24:25], v[74:75], v[24:25] op_sel_hi:[0,1]
	v_pk_mul_f32 v[22:23], v[74:75], v[22:23] op_sel_hi:[0,1]
	v_pk_mul_f32 v[20:21], v[74:75], v[20:21] op_sel_hi:[0,1]
	v_pk_mul_f32 v[18:19], v[74:75], v[18:19] op_sel_hi:[0,1]
	v_pk_mul_f32 v[16:17], v[74:75], v[16:17] op_sel_hi:[0,1]
.LBB0_665:
	v_add_f32_e32 v73, v153, v154
	v_add_f32_e32 v73, v156, v73
	v_add_f32_e32 v73, v155, v73
	v_add_f32_e32 v73, v158, v73
	v_add_f32_e32 v73, v157, v73
	v_add_f32_e32 v73, v160, v73
	v_add_f32_e32 v73, v159, v73
	v_add_f32_e32 v73, v162, v73
	v_add_f32_e32 v73, v161, v73
	v_add_f32_e32 v73, v166, v73
	v_add_f32_e32 v73, v165, v73
	v_sub_f32_e32 v74, v174, v145
	v_add_f32_e32 v73, v164, v73
	v_exp_f32_e32 v74, v74
	v_sub_f32_e32 v75, v173, v145
	v_add_f32_e32 v73, v169, v73
	v_exp_f32_e32 v75, v75
	v_sub_f32_e32 v76, v171, v145
	v_add_f32_e32 v73, v168, v73
	v_exp_f32_e32 v76, v76
	v_sub_f32_e32 v77, v170, v145
	v_add_f32_e32 v73, v163, v73
	v_exp_f32_e32 v77, v77
	v_sub_f32_e32 v78, v167, v145
	v_add_f32_e32 v147, v147, v73
	v_exp_f32_e32 v78, v78
	v_sub_f32_e32 v79, v152, v145
	v_add_f32_e32 v73, v75, v74
	v_exp_f32_e32 v79, v79
	v_sub_f32_e32 v70, v70, v145
	v_add_f32_e32 v73, v76, v73
	v_exp_f32_e32 v152, v70
	v_sub_f32_e32 v69, v69, v145
	v_add_f32_e32 v73, v77, v73
	v_exp_f32_e32 v69, v69
	v_sub_f32_e32 v70, v172, v145
	v_add_f32_e32 v73, v78, v73
	v_exp_f32_e32 v153, v70
	v_sub_f32_e32 v70, v72, v145
	v_add_f32_e32 v73, v79, v73
	v_exp_f32_e32 v154, v70
	v_add_f32_e32 v70, v152, v73
	v_add_f32_e32 v70, v69, v70
	v_add_f32_e32 v70, v153, v70
	v_add_f32_e32 v155, v154, v70
	v_sub_f32_e32 v70, v71, v145
	v_exp_f32_e32 v156, v70
	v_cvt_pk_bf16_f32 v70, v74, v75
	v_cvt_pk_bf16_f32 v71, v76, v77
	v_cvt_pk_bf16_f32 v72, v78, v79
	v_cvt_pk_bf16_f32 v73, v152, v69
	v_sub_f32_e32 v67, v67, v145
	v_sub_f32_e32 v65, v65, v145
	v_mfma_f32_32x32x16_bf16 v[0:15], v[140:143], v[70:73], v[0:15]
	v_exp_f32_e32 v69, v67
	v_sub_f32_e32 v67, v68, v145
	v_exp_f32_e32 v74, v65
	v_sub_f32_e32 v65, v66, v145
	v_sub_f32_e32 v64, v64, v145
	v_exp_f32_e32 v68, v67
	s_add_i32 s9, s9, 32
	v_mfma_f32_32x32x16_bf16 v[16:31], v[136:139], v[70:73], v[16:31]
	v_exp_f32_e32 v70, v65
	v_exp_f32_e32 v71, v64
	v_cvt_pk_bf16_f32 v64, v153, v154
	v_cvt_pk_bf16_f32 v65, v156, v69
	v_cvt_pk_bf16_f32 v66, v68, v74
	v_cvt_pk_bf16_f32 v67, v70, v71
	v_add_f32_e32 v72, v156, v155
	v_add_f32_e32 v69, v69, v72
	v_mfma_f32_32x32x16_bf16 v[0:15], v[132:135], v[64:67], v[0:15]
	v_add_f32_e32 v68, v68, v69
	v_add_f32_e32 v68, v74, v68
	v_add_f32_e32 v68, v70, v68
	v_add_f32_e32 v68, v71, v68
	v_add_f32_e32 v144, v144, v68
	s_cmpk_eq_i32 s9, 0xe0
	v_mfma_f32_32x32x16_bf16 v[16:31], v[128:131], v[64:67], v[16:31]
	v_add_u32_e32 v64, s4, v149
	s_cbranch_scc1 .LBB0_667
	v_mov_b32_e32 v152, v150
	s_branch .LBB0_661

; __device__ __forceinline__ unsigned cvt_pk_bf16(float lo, float hi) { f32x2_c v = {lo, hi}; bf16x2_c b = __builtin_convertvector(v, bf16x2_c); return __builtin_bit_cast(unsigned, b); }
; template <class MB> __device__ __forceinline__ void la_soft(LA& st, f32x16& s, const TP& t, bf16x8& pf0, bf16x8& pf1) {
;     float mx = NEGBIG;
; #pragma unroll
;     for (int r = 0; r < 16; ++r) { s[r] = MB::apply(t, r, s[r]); mx = __builtin_fmaxf(mx, s[r]); }
;     { auto rr = __builtin_amdgcn_permlane32_swap(__float_as_uint(mx), __float_as_uint(mx), false, false); mx = __builtin_fmaxf(__uint_as_float(rr[0]), __uint_as_float(rr[1])); }
;     if (__any(mx > st.m)) { const float mn = __builtin_fmaxf(st.m, mx), alpha = __builtin_amdgcn_exp2f(st.m - mn); st.m = mn; st.l *= alpha; st.o0 *= alpha; st.o1 *= alpha; }
;     float rs = 0.f;
; #pragma unroll
;     for (int r = 0; r < 16; ++r) { s[r] = __builtin_amdgcn_exp2f(s[r] - st.m); rs += s[r]; }
;     st.l += rs;
;     u32x4 p0, p1;
; #pragma unroll
;     for (int e = 0; e < 4; ++e) { p0[e] = cvt_pk_bf16(s[2 * e], s[2 * e + 1]); p1[e] = cvt_pk_bf16(s[8 + 2 * e], s[8 + 2 * e + 1]); }
;     pf0 = __builtin_bit_cast(bf16x8, p0); pf1 = __builtin_bit_cast(bf16x8, p1);
; }
; template <class MB, int V1, class VS> __device__ __forceinline__ void la_step2(LA& sa, LA& sb, const bf16x8 (&qa)[4], const bf16x8 (&qb)[4], Frag& f, const char* kb, const VS& vs, const TP& t, const TP& n) {
;     bf16x8 pa0, pa1;
;     { f32x16 s0 = zero16();
; #pragma unroll
;       for (int d0 = 0; d0 < 4; ++d0) s0 = __builtin_amdgcn_mfma_f32_32x32x16_bf16(f.k[d0], qa[d0], s0, 0, 0, 0);
;       la_soft<MB>(sa, s0, t, pa0, pa1); }
.LBB0_672:
	v_add_f32_e32 v73, v198, v199
	v_add_f32_e32 v73, v201, v73
	v_add_f32_e32 v73, v200, v73
	v_add_f32_e32 v73, v203, v73
	v_add_f32_e32 v73, v202, v73
	v_add_f32_e32 v73, v205, v73
	v_add_f32_e32 v73, v204, v73
	v_add_f32_e32 v73, v207, v73
	v_add_f32_e32 v73, v206, v73
	v_add_f32_e32 v73, v211, v73
	v_add_f32_e32 v73, v210, v73
	v_add_f32_e32 v73, v209, v73
	v_add_f32_e32 v73, v208, v73
	v_add_f32_e32 v73, v213, v73
	v_add_f32_e32 v73, v212, v73
	v_add_f32_e32 v193, v193, v73
	v_sub_f32_e32 v73, v219, v191
	v_exp_f32_e32 v74, v73
	v_sub_f32_e32 v73, v218, v191
	v_exp_f32_e32 v75, v73
	v_sub_f32_e32 v77, v216, v191
	v_exp_f32_e32 v77, v77
	v_sub_f32_e32 v78, v215, v191
	v_exp_f32_e32 v78, v78
	v_sub_f32_e32 v79, v214, v191
	v_exp_f32_e32 v79, v79
	v_sub_f32_e32 v197, v197, v191
	v_add_f32_e32 v76, v75, v74
	v_exp_f32_e32 v197, v197
	v_sub_f32_e32 v69, v69, v191
	v_add_f32_e32 v76, v77, v76
	v_exp_f32_e32 v198, v69
	v_sub_f32_e32 v68, v68, v191
	v_add_f32_e32 v76, v78, v76
	v_exp_f32_e32 v199, v68
	v_sub_f32_e32 v68, v217, v191
	v_add_f32_e32 v76, v79, v76
	v_exp_f32_e32 v200, v68
	v_sub_f32_e32 v68, v72, v191
	v_add_f32_e32 v76, v197, v76
	v_exp_f32_e32 v72, v68
	v_add_f32_e32 v68, v198, v76
	v_add_f32_e32 v68, v199, v68
	v_add_f32_e32 v68, v200, v68
	v_add_f32_e32 v76, v72, v68
	v_sub_f32_e32 v68, v71, v191
	v_exp_f32_e32 v201, v68
	v_sub_f32_e32 v68, v70, v191
	v_exp_f32_e32 v202, v68
	v_cvt_pk_bf16_f32 v68, v74, v75
	v_cvt_pk_bf16_f32 v69, v77, v78
	v_cvt_pk_bf16_f32 v70, v79, v197
	v_cvt_pk_bf16_f32 v71, v198, v199
	v_sub_f32_e32 v65, v65, v191
	v_add_f32_e32 v74, v201, v76
	v_mfma_f32_32x32x16_bf16 v[16:31], v[140:143], v[68:71], v[16:31]
	v_sub_f32_e32 v67, v67, v191
	v_exp_f32_e32 v76, v65
	v_sub_f32_e32 v65, v66, v191
	v_sub_f32_e32 v64, v64, v191
	v_exp_f32_e32 v75, v67
	v_add_f32_e32 v74, v202, v74
	s_lshl_b32 s8, s8, 1
	v_mfma_f32_32x32x16_bf16 v[0:15], v[136:139], v[68:71], v[0:15]
	v_exp_f32_e32 v68, v65
	v_exp_f32_e32 v69, v64
	v_cvt_pk_bf16_f32 v64, v200, v72
	v_cvt_pk_bf16_f32 v65, v201, v202
	v_cvt_pk_bf16_f32 v66, v75, v76
	v_cvt_pk_bf16_f32 v67, v68, v69
	v_add_f32_e32 v70, v75, v74
	v_add_f32_e32 v70, v76, v70
	v_mfma_f32_32x32x16_bf16 v[16:31], v[132:135], v[64:67], v[16:31]
	v_add_f32_e32 v68, v68, v70
	s_andn2_b32 s8, s8, 63
	v_add_f32_e32 v68, v69, v68
	s_addk_i32 s12, 0x80
	v_add_u32_e32 v73, s8, v194
	v_add_f32_e32 v190, v190, v68
	s_cmpk_eq_i32 s12, 0x500
	v_mfma_f32_32x32x16_bf16 v[0:15], v[128:131], v[64:67], v[0:15]
	s_cbranch_scc1 .LBB0_677
.LBB0_673:
	v_lshlrev_b32_e32 v64, 1, v73
	v_ashrrev_i32_e32 v65, 31, v64
	v_lshl_add_u64 v[64:65], s[6:7], 0, v[64:65]
	v_add_co_u32_e32 v66, vcc, s80, v64
	s_add_i32 s8, s11, s13
	s_nop 0
	v_addc_co_u32_e32 v67, vcc, 0, v65, vcc
	global_load_dwordx4 v[128:131], v[66:67], off offset:2080
	global_load_dwordx4 v[136:139], v[66:67], off offset:2048
	global_load_dwordx4 v[132:135], v[64:65], off offset:32
	global_load_dwordx4 v[140:143], v[64:65], off
	s_cmpk_lt_u32 s8, 0x4000
	s_cselect_b64 s[8:9], -1, 0
	s_cmpk_lg_i32 s12, 0x480
	s_cselect_b64 s[14:15], -1, 0
	v_add_u32_e32 v197, s12, v195
	s_and_b64 vcc, s[14:15], s[8:9]
	v_add_u32_e32 v64, 0x80, v197
	v_mov_b32_e32 v65, s53
	v_cndmask_b32_e32 v212, v65, v64, vcc
	ds_read2_b32 v[200:201], v212 offset1:1
	s_waitcnt vmcnt(7)
	s_nop 0
	v_mfma_f32_32x32x16_bf16 v[64:79], v[124:127], v[80:83], 0
	s_waitcnt vmcnt(6)
	v_mfma_f32_32x32x16_bf16 v[64:79], v[120:123], v[84:87], v[64:79]
	s_waitcnt vmcnt(5)
	v_mfma_f32_32x32x16_bf16 v[64:79], v[116:119], v[96:99], v[64:79]
	s_waitcnt vmcnt(4)
	v_mfma_f32_32x32x16_bf16 v[64:79], v[112:115], v[100:103], v[64:79]
	s_waitcnt lgkmcnt(0)
	s_nop 10
	v_add_f32_e32 v199, v64, v200
	v_add_f32_e32 v198, v65, v201
	ds_read2_b32 v[64:65], v212 offset0:2 offset1:3
	v_max3_f32 v202, v199, s2, v198
	s_waitcnt lgkmcnt(0)
	v_add_f32_e32 v201, v66, v64
	v_add_f32_e32 v200, v67, v65
	ds_read2_b32 v[64:65], v212 offset0:4 offset1:5
	v_max3_f32 v66, v202, v201, v200
	s_waitcnt lgkmcnt(0)
	v_add_f32_e32 v203, v68, v64
	v_add_f32_e32 v202, v69, v65
	ds_read2_b32 v[64:65], v212 offset0:6 offset1:7
	v_max3_f32 v66, v66, v203, v202
	s_waitcnt lgkmcnt(0)
	v_add_f32_e32 v205, v70, v64
	v_add_f32_e32 v204, v71, v65
	ds_read2_b32 v[64:65], v212 offset0:16 offset1:17
	v_max3_f32 v66, v66, v205, v204
	s_waitcnt lgkmcnt(0)
	v_add_f32_e32 v207, v72, v64
	v_add_f32_e32 v206, v73, v65
	ds_read2_b32 v[64:65], v212 offset0:18 offset1:19
	v_max3_f32 v66, v66, v207, v206
	s_waitcnt lgkmcnt(0)
	v_add_f32_e32 v211, v74, v64
	v_add_f32_e32 v210, v75, v65
	ds_read2_b32 v[64:65], v212 offset0:20 offset1:21
	v_max3_f32 v66, v66, v211, v210
	s_waitcnt lgkmcnt(0)
	v_add_f32_e32 v209, v76, v64
	v_add_f32_e32 v208, v77, v65
	ds_read2_b32 v[64:65], v212 offset0:22 offset1:23
	v_max3_f32 v66, v66, v209, v208
	s_waitcnt lgkmcnt(0)
	v_add_f32_e32 v213, v78, v64
	v_add_f32_e32 v212, v79, v65
	v_max3_f32 v64, v66, v213, v212
	v_mov_b32_e32 v65, v64
	s_nop 1
	v_permlane32_swap_b32_e32 v64, v65
	v_max_f32_e32 v64, v64, v65
	v_cmp_gt_f32_e32 vcc, v64, v196
	s_cbranch_vccz .LBB0_675
	v_max_f32_e32 v64, v64, v64
	v_max_f32_e32 v65, v196, v196
	v_max_f32_e32 v65, v65, v64
	v_sub_f32_e32 v64, v196, v65
	v_exp_f32_e32 v64, v64
	v_mov_b32_e32 v196, v65
	v_mul_f32_e32 v193, v193, v64
	v_pk_mul_f32 v[62:63], v[62:63], v[64:65] op_sel_hi:[1,0]
	v_pk_mul_f32 v[60:61], v[60:61], v[64:65] op_sel_hi:[1,0]
	v_pk_mul_f32 v[58:59], v[58:59], v[64:65] op_sel_hi:[1,0]
	v_pk_mul_f32 v[56:57], v[56:57], v[64:65] op_sel_hi:[1,0]
	v_pk_mul_f32 v[54:55], v[54:55], v[64:65] op_sel_hi:[1,0]
	v_pk_mul_f32 v[52:53], v[52:53], v[64:65] op_sel_hi:[1,0]
	v_pk_mul_f32 v[50:51], v[50:51], v[64:65] op_sel_hi:[1,0]
	v_pk_mul_f32 v[48:49], v[48:49], v[64:65] op_sel_hi:[1,0]
	v_pk_mul_f32 v[46:47], v[46:47], v[64:65] op_sel_hi:[1,0]
	v_pk_mul_f32 v[44:45], v[44:45], v[64:65] op_sel_hi:[1,0]
	v_pk_mul_f32 v[42:43], v[42:43], v[64:65] op_sel_hi:[1,0]
	v_pk_mul_f32 v[40:41], v[40:41], v[64:65] op_sel_hi:[1,0]
	v_pk_mul_f32 v[38:39], v[38:39], v[64:65] op_sel_hi:[1,0]
	v_pk_mul_f32 v[36:37], v[36:37], v[64:65] op_sel_hi:[1,0]
	v_pk_mul_f32 v[34:35], v[34:35], v[64:65] op_sel_hi:[1,0]
	v_pk_mul_f32 v[32:33], v[32:33], v[64:65] op_sel_hi:[1,0]
; #define LAS __attribute__((address_space(3)))
; __host__ __device__ __forceinline__ int vt_off(int d, int p) { return (d >> 1) * VTPP + (p >> 5) * 64 + (d & 1) * 32 + (p & 31); }
; template <class MB, int V1, class VS> __device__ __forceinline__ void la_step2(LA& sa, LA& sb, const bf16x8 (&qa)[4], const bf16x8 (&qb)[4], Frag& f, const char* kb, const VS& vs, const TP& t, const TP& n) {
;     ...
;     f32x16 s1 = zero16();
; #pragma unroll
;     for (int d0 = 0; d0 < 4; ++d0) s1 = __builtin_amdgcn_mfma_f32_32x32x16_bf16(f.k[d0], qb[d0], s1, 0, 0, 0);
;     la_loadK(f, kb, n);
;     sa.o0 = __builtin_amdgcn_mfma_f32_32x32x16_bf16(f.v[0], pa0, sa.o0, 0, 0, 0); sa.o1 = __builtin_amdgcn_mfma_f32_32x32x16_bf16(f.v[2], pa0, sa.o1, 0, 0, 0);
;     sa.o0 = __builtin_amdgcn_mfma_f32_32x32x16_bf16(f.v[1], pa1, sa.o0, 0, 0, 0); sa.o1 = __builtin_amdgcn_mfma_f32_32x32x16_bf16(f.v[3], pa1, sa.o1, 0, 0, 0);
;     { bf16x8 pb0, pb1; const TP tb = MB::second(t);
;       la_soft<MB>(sb, s1, tb, pb0, pb1);
;       sb.o0 = __builtin_amdgcn_mfma_f32_32x32x16_bf16(f.v[0], pb0, sb.o0, 0, 0, 0); sb.o1 = __builtin_amdgcn_mfma_f32_32x32x16_bf16(f.v[2], pb0, sb.o1, 0, 0, 0);
;       sb.o0 = __builtin_amdgcn_mfma_f32_32x32x16_bf16(f.v[1], pb1, sb.o0, 0, 0, 0); sb.o1 = __builtin_amdgcn_mfma_f32_32x32x16_bf16(f.v[3], pb1, sb.o1, 0, 0, 0); }
; __global__ void __launch_bounds__(NWAVES * 64, 2) mk_fwd(Args args) {
;     ...
;                 auto tile = [&](int i) -> TP { const int t0r = q0 - 128 + 32 * i; const bool ok = t0r >= 0 && t0r < SEQ; const int t0 = ok ? t0r : q0; TP t;
;                     t.koff = ((unsigned)(t0 + lam) * PP + kc) * 2u; t.voff = (unsigned)(vt_off(vd, t0 + 8 * hi) * 2);
;                     t.tp = (ok && i <= 8) ? (const LAS char*)(tabA + (TABA_C + t0 + 8 * hi - tqa)) : negp;
;                     t.tp2 = (ok && i >= 1) ? (const LAS char*)(tabA + (TABA_C + t0 + 8 * hi - tqb)) : negp; t.cb = 0; return t; };
.LBB0_675:
	s_cmp_lg_u32 s12, 0
	s_cselect_b64 s[14:15], -1, 0
	s_and_b64 vcc, s[14:15], s[8:9]
	s_add_i32 s13, s13, 32
	s_cmpk_lg_i32 s12, 0x480
	s_cselect_b32 s8, s13, 0xa0
	s_add_i32 s8, s8, s11
	s_cmpk_lt_u32 s8, 0x4000
	s_cselect_b32 s8, s8, s11
	v_or_b32_e32 v64, s8, v185
	v_mul_lo_u32 v64, v64, s67
	v_add_lshl_u32 v219, v64, v192, 1
	v_mov_b32_e32 v218, s53
	v_cndmask_b32_e32 v226, v218, v197, vcc
	s_nop 0
	v_mfma_f32_32x32x16_bf16 v[64:79], v[124:127], v[88:91], 0
	v_sub_f32_e32 v124, v199, v196
	v_exp_f32_e32 v199, v124
	v_sub_f32_e32 v124, v198, v196
	v_exp_f32_e32 v198, v124
	v_sub_f32_e32 v124, v201, v196
	v_exp_f32_e32 v201, v124
	v_sub_f32_e32 v124, v200, v196
	v_mfma_f32_32x32x16_bf16 v[64:79], v[120:123], v[92:95], v[64:79]
	v_sub_f32_e32 v120, v203, v196
	v_exp_f32_e32 v203, v120
	v_sub_f32_e32 v120, v202, v196
	v_exp_f32_e32 v202, v120
	v_sub_f32_e32 v120, v205, v196
	v_exp_f32_e32 v200, v124
	v_exp_f32_e32 v205, v120
	v_mfma_f32_32x32x16_bf16 v[64:79], v[116:119], v[104:107], v[64:79]
	v_sub_f32_e32 v116, v204, v196
	v_exp_f32_e32 v204, v116
	v_sub_f32_e32 v116, v207, v196
	v_exp_f32_e32 v207, v116
	v_sub_f32_e32 v116, v206, v196
	v_exp_f32_e32 v206, v116
	v_sub_f32_e32 v116, v211, v196
	v_exp_f32_e32 v211, v116
	v_sub_f32_e32 v116, v209, v196
	v_exp_f32_e32 v209, v116
	v_sub_f32_e32 v116, v208, v196
	v_mfma_f32_32x32x16_bf16 v[64:79], v[112:115], v[108:111], v[64:79]
	v_sub_f32_e32 v112, v210, v196
	v_exp_f32_e32 v208, v116
	v_sub_f32_e32 v116, v213, v196
	v_exp_f32_e32 v210, v112
	v_cvt_pk_bf16_f32 v112, v199, v198
	v_cvt_pk_bf16_f32 v113, v201, v200
	v_cvt_pk_bf16_f32 v114, v203, v202
	v_cvt_pk_bf16_f32 v115, v205, v204
	v_exp_f32_e32 v213, v116
	v_sub_f32_e32 v116, v212, v196
	s_waitcnt vmcnt(0)
	v_mfma_f32_32x32x16_bf16 v[48:63], v[140:143], v[112:115], v[48:63]
	v_exp_f32_e32 v212, v116
	global_load_dwordx4 v[124:127], v219, s[74:75]
	global_load_dwordx4 v[120:123], v219, s[74:75] offset:32
	v_cvt_pk_bf16_f32 v214, v207, v206
	v_cvt_pk_bf16_f32 v215, v211, v210
	v_cvt_pk_bf16_f32 v216, v209, v208
	v_cvt_pk_bf16_f32 v217, v213, v212
	v_mfma_f32_32x32x16_bf16 v[32:47], v[136:139], v[112:115], v[32:47]
	global_load_dwordx4 v[116:119], v219, s[74:75] offset:64
	global_load_dwordx4 v[112:115], v219, s[74:75] offset:96
	ds_read2_b32 v[220:221], v226 offset1:1
	s_waitcnt lgkmcnt(0)
	v_add_f32_e32 v219, v64, v220
	v_mfma_f32_32x32x16_bf16 v[48:63], v[132:135], v[214:217], v[48:63]
	v_add_f32_e32 v218, v65, v221
	v_max3_f32 v64, v219, s2, v218
	v_mfma_f32_32x32x16_bf16 v[32:47], v[128:131], v[214:217], v[32:47]
	ds_read2_b32 v[214:215], v226 offset0:2 offset1:3
	ds_read2_b32 v[222:223], v226 offset0:4 offset1:5
	ds_read2_b32 v[224:225], v226 offset0:6 offset1:7
	s_waitcnt lgkmcnt(2)
	v_add_f32_e32 v216, v66, v214
	v_add_f32_e32 v215, v67, v215
	v_max3_f32 v64, v64, v216, v215
	s_waitcnt lgkmcnt(1)
	v_add_f32_e32 v214, v68, v222
	v_add_f32_e32 v197, v69, v223
	v_max3_f32 v66, v64, v214, v197
	ds_read2_b32 v[64:65], v226 offset0:16 offset1:17
	s_waitcnt lgkmcnt(1)
	v_add_f32_e32 v69, v70, v224
	v_add_f32_e32 v68, v71, v225
	v_max3_f32 v70, v66, v69, v68
	ds_read2_b32 v[66:67], v226 offset0:18 offset1:19
	ds_read2_b32 v[220:221], v226 offset0:20 offset1:21
	ds_read2_b32 v[222:223], v226 offset0:22 offset1:23
	s_waitcnt lgkmcnt(3)
	v_add_f32_e32 v217, v72, v64
	v_add_f32_e32 v72, v73, v65
	v_max3_f32 v64, v70, v217, v72
	s_waitcnt lgkmcnt(2)
	v_add_f32_e32 v71, v74, v66
	v_add_f32_e32 v70, v75, v67
	v_max3_f32 v64, v64, v71, v70
	s_waitcnt lgkmcnt(1)
	v_add_f32_e32 v67, v76, v220
	v_add_f32_e32 v65, v77, v221
	v_max3_f32 v73, v64, v67, v65
	s_waitcnt lgkmcnt(0)
	v_add_f32_e32 v66, v78, v222
	v_add_f32_e32 v64, v79, v223
	v_max3_f32 v73, v73, v66, v64
	v_mov_b32_e32 v74, v73
	s_nop 1
	v_permlane32_swap_b32_e32 v73, v74
	v_max_f32_e32 v73, v73, v74
	v_cmp_gt_f32_e32 vcc, v73, v191
	s_cbranch_vccz .LBB0_672
	v_max_f32_e32 v73, v73, v73
	v_max_f32_e32 v74, v191, v191
	v_max_f32_e32 v73, v74, v73
	v_sub_f32_e32 v74, v191, v73
	v_exp_f32_e32 v74, v74
	v_mov_b32_e32 v191, v73
	v_mul_f32_e32 v190, v190, v74
	v_pk_mul_f32 v[30:31], v[30:31], v[74:75] op_sel_hi:[1,0]
	v_pk_mul_f32 v[28:29], v[28:29], v[74:75] op_sel_hi:[1,0]
	v_pk_mul_f32 v[26:27], v[26:27], v[74:75] op_sel_hi:[1,0]
	v_pk_mul_f32 v[24:25], v[24:25], v[74:75] op_sel_hi:[1,0]
	v_pk_mul_f32 v[22:23], v[22:23], v[74:75] op_sel_hi:[1,0]
	v_pk_mul_f32 v[20:21], v[20:21], v[74:75] op_sel_hi:[1,0]
	v_pk_mul_f32 v[18:19], v[18:19], v[74:75] op_sel_hi:[1,0]
	v_pk_mul_f32 v[16:17], v[16:17], v[74:75] op_sel_hi:[1,0]
	v_pk_mul_f32 v[14:15], v[14:15], v[74:75] op_sel_hi:[1,0]
	v_pk_mul_f32 v[12:13], v[12:13], v[74:75] op_sel_hi:[1,0]
	v_pk_mul_f32 v[10:11], v[10:11], v[74:75] op_sel_hi:[1,0]
	v_pk_mul_f32 v[8:9], v[8:9], v[74:75] op_sel_hi:[1,0]
	v_pk_mul_f32 v[6:7], v[6:7], v[74:75] op_sel_hi:[1,0]
	v_pk_mul_f32 v[4:5], v[4:5], v[74:75] op_sel_hi:[1,0]
	v_pk_mul_f32 v[2:3], v[2:3], v[74:75] op_sel_hi:[1,0]
	v_pk_mul_f32 v[0:1], v[0:1], v[74:75] op_sel_hi:[1,0]
	s_branch .LBB0_672

; #define LAS __attribute__((address_space(3)))
; __host__ __device__ __forceinline__ int vt_off(int d, int p) { return (d >> 1) * VTPP + (p >> 5) * 64 + (d & 1) * 32 + (p & 31); }
; #define LA_RUN2(NT, TILE, MB, V1, KB, VS_) do { Frag f_; { const TP t0_ = TILE(0); la_loadK(f_, KB, t0_); (VS_).template load<V1>(f_, t0_.voff); } \
;     _Pragma("unroll 1") for (int i_ = 0; i_ < (NT); ++i_) { const TP t_ = TILE(i_); const TP n_ = TILE(i_ + 1 < (NT) ? i_ + 1 : i_); la_step2<MB, V1>(sa, sb, qa, qb, f_, KB, VS_, t_, n_); } } while (0)
; template <class MB, int V1, class VS> __device__ __forceinline__ void la_step2(LA& sa, LA& sb, const bf16x8 (&qa)[4], const bf16x8 (&qb)[4], Frag& f, const char* kb, const VS& vs, const TP& t, const TP& n) {
;     bf16x8 pa0, pa1;
;     { f32x16 s0 = zero16();
; #pragma unroll
;       for (int d0 = 0; d0 < 4; ++d0) s0 = __builtin_amdgcn_mfma_f32_32x32x16_bf16(f.k[d0], qa[d0], s0, 0, 0, 0);
;       la_soft<MB>(sa, s0, t, pa0, pa1); }
; __global__ void __launch_bounds__(NWAVES * 64, 2) mk_fwd(Args args) {
;     ...
;                 auto tile = [&](int i) -> TP { const int kr = rsa + i, krc = kr > 255 ? 255 : kr, t0 = 64 * krc + 32 * qh; const bool va = i <= 7, vb = kr >= rsb && kr < rsb + 8; TP t;
;                     t.koff = ((unsigned)(t0 + lam) * PP + kc) * 2u; t.voff = (unsigned)(vt_off(vd, t0 + 8 * hi) * 2);
;                     const LAS char* bp = bb0 + kr * 512;
;                     t.tp = va ? bp : negp; t.tp2 = vb ? bp - 512 : negp; t.cb = cbr; return t; };
;                 LA_RUN2(9, tile, MB_B, 32, PB, vs);
.LBB0_678:
	v_lshl_add_u32 v64, s41, 2, v165
	v_ashrrev_i32_e32 v65, 31, v64
	v_lshl_add_u64 v[64:65], s[56:57], 0, v[64:65]
	v_add_co_u32_e32 v66, vcc, s80, v64
	s_cmp_eq_u32 s60, 8
	s_nop 0
	v_addc_co_u32_e32 v67, vcc, 0, v65, vcc
	global_load_dwordx4 v[128:131], v[66:67], off offset:2080
	global_load_dwordx4 v[136:139], v[66:67], off offset:2048
	global_load_dwordx4 v[132:135], v[64:65], off offset:32
	global_load_dwordx4 v[140:143], v[64:65], off
	s_cselect_b64 s[40:41], -1, 0
	v_add_u32_e32 v166, 0x200, v167
	v_mov_b32_e32 v64, s53
	v_cndmask_b32_e64 v183, v166, v64, s[40:41]
	ds_read2_b32 v[168:169], v183 offset1:1
	s_waitcnt vmcnt(7)
	s_nop 0
	v_mfma_f32_32x32x16_bf16 v[64:79], v[124:127], v[96:99], 0
	s_waitcnt vmcnt(6)
	v_mfma_f32_32x32x16_bf16 v[64:79], v[120:123], v[100:103], v[64:79]
	s_waitcnt vmcnt(5)
	v_mfma_f32_32x32x16_bf16 v[64:79], v[116:119], v[104:107], v[64:79]
	s_waitcnt vmcnt(4)
	v_mfma_f32_32x32x16_bf16 v[64:79], v[112:115], v[108:111], v[64:79]
	s_waitcnt lgkmcnt(0)
	s_nop 10
	v_add_f32_e32 v64, v64, v168
	v_cndmask_b32_e64 v168, v232, v64, s[6:7]
	v_add_f32_e32 v64, v65, v169
	v_cndmask_b32_e64 v169, v232, v64, s[8:9]
	ds_read2_b32 v[64:65], v183 offset0:2 offset1:3
	v_max3_f32 v172, v168, s2, v169
	s_waitcnt lgkmcnt(0)
	v_add_f32_e32 v64, v66, v64
	v_cndmask_b32_e64 v170, v232, v64, s[10:11]
	v_add_f32_e32 v64, v67, v65
	v_cndmask_b32_e64 v171, v232, v64, s[12:13]
	ds_read2_b32 v[64:65], v183 offset0:4 offset1:5
	v_max3_f32 v66, v172, v170, v171
	s_waitcnt lgkmcnt(0)
	v_add_f32_e32 v64, v68, v64
	v_cndmask_b32_e64 v172, v232, v64, s[14:15]
	v_add_f32_e32 v64, v69, v65
	v_cndmask_b32_e64 v173, v232, v64, s[16:17]
	ds_read2_b32 v[64:65], v183 offset0:6 offset1:7
	v_max3_f32 v66, v66, v172, v173
	s_waitcnt lgkmcnt(0)
	v_add_f32_e32 v64, v70, v64
	v_cndmask_b32_e64 v175, v232, v64, s[18:19]
	v_add_f32_e32 v64, v71, v65
	v_cndmask_b32_e64 v174, v232, v64, s[20:21]
	ds_read2_b32 v[64:65], v183 offset0:16 offset1:17
	v_max3_f32 v66, v66, v175, v174
	s_waitcnt lgkmcnt(0)
	v_add_f32_e32 v64, v72, v64
	v_cndmask_b32_e64 v176, v232, v64, s[22:23]
	v_add_f32_e32 v64, v73, v65
	v_cndmask_b32_e64 v177, v232, v64, s[24:25]
	ds_read2_b32 v[64:65], v183 offset0:18 offset1:19
	v_max3_f32 v66, v66, v176, v177
	s_waitcnt lgkmcnt(0)
	v_add_f32_e32 v64, v74, v64
	v_cndmask_b32_e64 v179, v232, v64, s[26:27]
	v_add_f32_e32 v64, v75, v65
	v_cndmask_b32_e64 v178, v232, v64, s[28:29]
	ds_read2_b32 v[64:65], v183 offset0:20 offset1:21
	v_max3_f32 v66, v66, v179, v178
	s_waitcnt lgkmcnt(0)
	v_add_f32_e32 v64, v76, v64
	v_cndmask_b32_e64 v180, v232, v64, s[30:31]
	v_add_f32_e32 v64, v77, v65
	v_cndmask_b32_e64 v182, v232, v64, s[34:35]
	ds_read2_b32 v[64:65], v183 offset0:22 offset1:23
	v_max3_f32 v66, v66, v180, v182
	s_waitcnt lgkmcnt(0)
	v_add_f32_e32 v64, v78, v64
	v_cndmask_b32_e64 v183, v232, v64, s[36:37]
	v_add_f32_e32 v64, v79, v65
	v_cndmask_b32_e64 v190, v232, v64, s[38:39]
	v_max3_f32 v64, v66, v183, v190
	v_mov_b32_e32 v65, v64
	s_nop 1
	v_permlane32_swap_b32_e32 v64, v65
	v_max_f32_e32 v64, v64, v65
	v_cmp_gt_f32_e32 vcc, v64, v162
	s_cbranch_vccz .LBB0_680
	v_max_f32_e32 v64, v64, v64
	v_max_f32_e32 v65, v162, v162
	v_max_f32_e32 v65, v65, v64
	v_sub_f32_e32 v64, v162, v65
	v_exp_f32_e32 v64, v64
	v_mov_b32_e32 v162, v65
	v_mul_f32_e32 v157, v157, v64
	v_pk_mul_f32 v[62:63], v[62:63], v[64:65] op_sel_hi:[1,0]
	v_pk_mul_f32 v[60:61], v[60:61], v[64:65] op_sel_hi:[1,0]
	v_pk_mul_f32 v[58:59], v[58:59], v[64:65] op_sel_hi:[1,0]
	v_pk_mul_f32 v[56:57], v[56:57], v[64:65] op_sel_hi:[1,0]
	v_pk_mul_f32 v[54:55], v[54:55], v[64:65] op_sel_hi:[1,0]
	v_pk_mul_f32 v[52:53], v[52:53], v[64:65] op_sel_hi:[1,0]
	v_pk_mul_f32 v[50:51], v[50:51], v[64:65] op_sel_hi:[1,0]
	v_pk_mul_f32 v[48:49], v[48:49], v[64:65] op_sel_hi:[1,0]
	v_pk_mul_f32 v[46:47], v[46:47], v[64:65] op_sel_hi:[1,0]
	v_pk_mul_f32 v[44:45], v[44:45], v[64:65] op_sel_hi:[1,0]
	v_pk_mul_f32 v[42:43], v[42:43], v[64:65] op_sel_hi:[1,0]
	v_pk_mul_f32 v[40:41], v[40:41], v[64:65] op_sel_hi:[1,0]
	v_pk_mul_f32 v[38:39], v[38:39], v[64:65] op_sel_hi:[1,0]
	v_pk_mul_f32 v[36:37], v[36:37], v[64:65] op_sel_hi:[1,0]
	v_pk_mul_f32 v[34:35], v[34:35], v[64:65] op_sel_hi:[1,0]
	v_pk_mul_f32 v[32:33], v[32:33], v[64:65] op_sel_hi:[1,0]
; #define LAS __attribute__((address_space(3)))
; __host__ __device__ __forceinline__ int vt_off(int d, int p) { return (d >> 1) * VTPP + (p >> 5) * 64 + (d & 1) * 32 + (p & 31); }
; template <class MB, int V1, class VS> __device__ __forceinline__ void la_step2(LA& sa, LA& sb, const bf16x8 (&qa)[4], const bf16x8 (&qb)[4], Frag& f, const char* kb, const VS& vs, const TP& t, const TP& n) {
;     ...
;     f32x16 s1 = zero16();
; #pragma unroll
;     for (int d0 = 0; d0 < 4; ++d0) s1 = __builtin_amdgcn_mfma_f32_32x32x16_bf16(f.k[d0], qb[d0], s1, 0, 0, 0);
;     la_loadK(f, kb, n);
;     sa.o0 = __builtin_amdgcn_mfma_f32_32x32x16_bf16(f.v[0], pa0, sa.o0, 0, 0, 0); sa.o1 = __builtin_amdgcn_mfma_f32_32x32x16_bf16(f.v[2], pa0, sa.o1, 0, 0, 0);
;     sa.o0 = __builtin_amdgcn_mfma_f32_32x32x16_bf16(f.v[1], pa1, sa.o0, 0, 0, 0); sa.o1 = __builtin_amdgcn_mfma_f32_32x32x16_bf16(f.v[3], pa1, sa.o1, 0, 0, 0);
;     { bf16x8 pb0, pb1; const TP tb = MB::second(t);
;       la_soft<MB>(sb, s1, tb, pb0, pb1);
;       sb.o0 = __builtin_amdgcn_mfma_f32_32x32x16_bf16(f.v[0], pb0, sb.o0, 0, 0, 0); sb.o1 = __builtin_amdgcn_mfma_f32_32x32x16_bf16(f.v[2], pb0, sb.o1, 0, 0, 0);
;       sb.o0 = __builtin_amdgcn_mfma_f32_32x32x16_bf16(f.v[1], pb1, sb.o0, 0, 0, 0); sb.o1 = __builtin_amdgcn_mfma_f32_32x32x16_bf16(f.v[3], pb1, sb.o1, 0, 0, 0); }
; __global__ void __launch_bounds__(NWAVES * 64, 2) mk_fwd(Args args) {
;     ...
;                 auto tile = [&](int i) -> TP { const int kr = rsa + i, krc = kr > 255 ? 255 : kr, t0 = 64 * krc + 32 * qh; const bool va = i <= 7, vb = kr >= rsb && kr < rsb + 8; TP t;
;                     t.koff = ((unsigned)(t0 + lam) * PP + kc) * 2u; t.voff = (unsigned)(vt_off(vd, t0 + 8 * hi) * 2);
;                     const LAS char* bp = bb0 + kr * 512;
;                     t.tp = va ? bp : negp; t.tp2 = vb ? bp - 512 : negp; t.cb = cbr; return t; };
.LBB0_680:
	s_add_i32 s0, s59, s60
	v_cmp_ge_u32_e32 vcc, s0, v159
	v_cmp_lt_u32_e64 s[44:45], s0, v153
	s_and_b64 vcc, vcc, s[44:45]
	s_add_i32 s60, s60, 1
	s_and_b64 s[40:41], s[40:41], exec
	s_cselect_b32 s0, 8, s60
	s_add_i32 s0, s0, s59
	s_min_i32 s0, s0, 0xff
	s_lshl_b32 s0, s0, 6
	s_or_b32 s41, s0, s55
	v_or_b32_e32 v64, s41, v185
	v_mul_lo_u32 v64, v64, s67
	v_add_lshl_u32 v196, v64, v161, 1
	v_mov_b32_e32 v191, s53
	v_cndmask_b32_e32 v204, v191, v167, vcc
	s_nop 0
	v_mfma_f32_32x32x16_bf16 v[64:79], v[124:127], v[80:83], 0
	v_sub_f32_e32 v124, v168, v162
	v_exp_f32_e32 v168, v124
	v_sub_f32_e32 v124, v169, v162
	v_exp_f32_e32 v169, v124
	v_sub_f32_e32 v124, v170, v162
	v_exp_f32_e32 v170, v124
	v_sub_f32_e32 v124, v171, v162
	v_mfma_f32_32x32x16_bf16 v[64:79], v[120:123], v[84:87], v[64:79]
	v_sub_f32_e32 v120, v172, v162
	v_exp_f32_e32 v172, v120
	v_sub_f32_e32 v120, v173, v162
	v_exp_f32_e32 v173, v120
	v_sub_f32_e32 v120, v175, v162
	v_exp_f32_e32 v171, v124
	v_exp_f32_e32 v175, v120
	v_mfma_f32_32x32x16_bf16 v[64:79], v[116:119], v[88:91], v[64:79]
	v_sub_f32_e32 v116, v174, v162
	v_exp_f32_e32 v174, v116
	v_sub_f32_e32 v116, v176, v162
	v_exp_f32_e32 v176, v116
	v_sub_f32_e32 v116, v177, v162
	v_exp_f32_e32 v177, v116
	v_sub_f32_e32 v116, v179, v162
	v_exp_f32_e32 v179, v116
	v_sub_f32_e32 v116, v180, v162
	v_exp_f32_e32 v180, v116
	v_sub_f32_e32 v116, v182, v162
	v_mfma_f32_32x32x16_bf16 v[64:79], v[112:115], v[92:95], v[64:79]
	v_sub_f32_e32 v112, v178, v162
	v_exp_f32_e32 v182, v116
	v_sub_f32_e32 v116, v183, v162
	v_exp_f32_e32 v178, v112
	v_cvt_pk_bf16_f32 v112, v168, v169
	v_cvt_pk_bf16_f32 v113, v170, v171
	v_cvt_pk_bf16_f32 v114, v172, v173
	v_cvt_pk_bf16_f32 v115, v175, v174
	v_exp_f32_e32 v183, v116
	v_sub_f32_e32 v116, v190, v162
	s_waitcnt vmcnt(0)
	v_mfma_f32_32x32x16_bf16 v[48:63], v[140:143], v[112:115], v[48:63]
	v_exp_f32_e32 v190, v116
	global_load_dwordx4 v[124:127], v196, s[74:75]
	global_load_dwordx4 v[120:123], v196, s[74:75] offset:32
	v_cvt_pk_bf16_f32 v192, v176, v177
	v_cvt_pk_bf16_f32 v193, v179, v178
	v_cvt_pk_bf16_f32 v194, v180, v182
	v_cvt_pk_bf16_f32 v195, v183, v190
	v_mfma_f32_32x32x16_bf16 v[32:47], v[136:139], v[112:115], v[32:47]
	global_load_dwordx4 v[116:119], v196, s[74:75] offset:64
	global_load_dwordx4 v[112:115], v196, s[74:75] offset:96
	ds_read2_b32 v[196:197], v204 offset1:1
	ds_read2_b32 v[198:199], v204 offset0:2 offset1:3
	ds_read2_b32 v[200:201], v204 offset0:4 offset1:5
	ds_read2_b32 v[202:203], v204 offset0:6 offset1:7
	s_waitcnt lgkmcnt(3)
	v_add_f32_e32 v64, v64, v196
	v_mfma_f32_32x32x16_bf16 v[48:63], v[132:135], v[192:195], v[48:63]
	v_mfma_f32_32x32x16_bf16 v[32:47], v[128:131], v[192:195], v[32:47]
	v_cndmask_b32_e64 v195, v232, v64, s[6:7]
	v_add_f32_e32 v64, v65, v197
	s_waitcnt lgkmcnt(2)
	v_add_f32_e32 v65, v66, v198
	v_cndmask_b32_e64 v194, v232, v65, s[10:11]
	v_add_f32_e32 v65, v67, v199
	v_cndmask_b32_e64 v193, v232, v64, s[8:9]
	v_cndmask_b32_e64 v191, v232, v65, s[12:13]
	s_waitcnt lgkmcnt(1)
	v_add_f32_e32 v65, v68, v200
	v_max3_f32 v64, v195, s2, v193
	v_cndmask_b32_e64 v192, v232, v65, s[14:15]
	v_add_f32_e32 v65, v69, v201
	v_max3_f32 v64, v64, v194, v191
	v_cndmask_b32_e64 v167, v232, v65, s[16:17]
	v_max3_f32 v66, v64, v192, v167
	s_waitcnt lgkmcnt(0)
	v_add_f32_e32 v64, v70, v202
	v_cndmask_b32_e64 v70, v232, v64, s[18:19]
	v_add_f32_e32 v64, v71, v203
	v_cndmask_b32_e64 v69, v232, v64, s[20:21]
	ds_read2_b32 v[64:65], v204 offset0:16 offset1:17
	v_max3_f32 v68, v66, v70, v69
	ds_read2_b32 v[66:67], v204 offset0:18 offset1:19
	ds_read2_b32 v[198:199], v204 offset0:20 offset1:21
	ds_read2_b32 v[200:201], v204 offset0:22 offset1:23
	s_waitcnt lgkmcnt(3)
	v_add_f32_e32 v64, v72, v64
	v_cndmask_b32_e64 v196, v232, v64, s[22:23]
	v_add_f32_e32 v64, v73, v65
	v_cndmask_b32_e64 v71, v232, v64, s[24:25]
	s_waitcnt lgkmcnt(2)
	v_add_f32_e32 v64, v74, v66
	v_cndmask_b32_e64 v72, v232, v64, s[26:27]
	v_add_f32_e32 v64, v75, v67
	v_max3_f32 v65, v68, v196, v71
	v_cndmask_b32_e64 v64, v232, v64, s[28:29]
	s_waitcnt lgkmcnt(1)
	v_add_f32_e32 v66, v76, v198
	v_add_f32_e32 v67, v77, v199
	v_max3_f32 v65, v65, v72, v64
	v_cndmask_b32_e64 v66, v232, v66, s[30:31]
	v_cndmask_b32_e64 v67, v232, v67, s[34:35]
	v_max3_f32 v73, v65, v66, v67
	s_waitcnt lgkmcnt(0)
	v_add_f32_e32 v65, v78, v200
	v_cndmask_b32_e64 v68, v232, v65, s[36:37]
	v_add_f32_e32 v65, v79, v201
	v_cndmask_b32_e64 v65, v232, v65, s[38:39]
	v_max3_f32 v73, v73, v68, v65
	v_mov_b32_e32 v74, v73
	s_nop 1
	v_permlane32_swap_b32_e32 v73, v74
	v_max_f32_e32 v73, v73, v74
	v_cmp_gt_f32_e32 vcc, v73, v145
	s_cbranch_vccz .LBB0_682
	v_max_f32_e32 v73, v73, v73
	v_max_f32_e32 v74, v145, v145
	v_max_f32_e32 v73, v74, v73
	v_sub_f32_e32 v74, v145, v73
	v_exp_f32_e32 v74, v74
	v_mov_b32_e32 v145, v73
	v_mul_f32_e32 v156, v156, v74
	v_pk_mul_f32 v[30:31], v[30:31], v[74:75] op_sel_hi:[1,0]
	v_pk_mul_f32 v[28:29], v[28:29], v[74:75] op_sel_hi:[1,0]
	v_pk_mul_f32 v[26:27], v[26:27], v[74:75] op_sel_hi:[1,0]
	v_pk_mul_f32 v[24:25], v[24:25], v[74:75] op_sel_hi:[1,0]
	v_pk_mul_f32 v[22:23], v[22:23], v[74:75] op_sel_hi:[1,0]
	v_pk_mul_f32 v[20:21], v[20:21], v[74:75] op_sel_hi:[1,0]
	v_pk_mul_f32 v[18:19], v[18:19], v[74:75] op_sel_hi:[1,0]
	v_pk_mul_f32 v[16:17], v[16:17], v[74:75] op_sel_hi:[1,0]
	v_pk_mul_f32 v[14:15], v[14:15], v[74:75] op_sel_hi:[1,0]
	v_pk_mul_f32 v[12:13], v[12:13], v[74:75] op_sel_hi:[1,0]
	v_pk_mul_f32 v[10:11], v[10:11], v[74:75] op_sel_hi:[1,0]
	v_pk_mul_f32 v[8:9], v[8:9], v[74:75] op_sel_hi:[1,0]
	v_pk_mul_f32 v[6:7], v[6:7], v[74:75] op_sel_hi:[1,0]
	v_pk_mul_f32 v[4:5], v[4:5], v[74:75] op_sel_hi:[1,0]
	v_pk_mul_f32 v[2:3], v[2:3], v[74:75] op_sel_hi:[1,0]
	v_pk_mul_f32 v[0:1], v[0:1], v[74:75] op_sel_hi:[1,0]
; __device__ __forceinline__ unsigned cvt_pk_bf16(float lo, float hi) { f32x2_c v = {lo, hi}; bf16x2_c b = __builtin_convertvector(v, bf16x2_c); return __builtin_bit_cast(unsigned, b); }
; template <class MB> __device__ __forceinline__ void la_soft(LA& st, f32x16& s, const TP& t, bf16x8& pf0, bf16x8& pf1) {
;     ...
;     float rs = 0.f;
; #pragma unroll
;     for (int r = 0; r < 16; ++r) { s[r] = __builtin_amdgcn_exp2f(s[r] - st.m); rs += s[r]; }
;     st.l += rs;
;     u32x4 p0, p1;
; #pragma unroll
;     for (int e = 0; e < 4; ++e) { p0[e] = cvt_pk_bf16(s[2 * e], s[2 * e + 1]); p1[e] = cvt_pk_bf16(s[8 + 2 * e], s[8 + 2 * e + 1]); }
;     pf0 = __builtin_bit_cast(bf16x8, p0); pf1 = __builtin_bit_cast(bf16x8, p1);
; }
; template <class MB, int V1, class VS> __device__ __forceinline__ void la_step2(LA& sa, LA& sb, const bf16x8 (&qa)[4], const bf16x8 (&qb)[4], Frag& f, const char* kb, const VS& vs, const TP& t, const TP& n) {
;     ...
;     { bf16x8 pb0, pb1; const TP tb = MB::second(t);
;       la_soft<MB>(sb, s1, tb, pb0, pb1);
;       sb.o0 = __builtin_amdgcn_mfma_f32_32x32x16_bf16(f.v[0], pb0, sb.o0, 0, 0, 0); sb.o1 = __builtin_amdgcn_mfma_f32_32x32x16_bf16(f.v[2], pb0, sb.o1, 0, 0, 0);
;       sb.o0 = __builtin_amdgcn_mfma_f32_32x32x16_bf16(f.v[1], pb1, sb.o0, 0, 0, 0); sb.o1 = __builtin_amdgcn_mfma_f32_32x32x16_bf16(f.v[3], pb1, sb.o1, 0, 0, 0); }
.LBB0_682:
	v_add_f32_e32 v73, v169, v168
	v_add_f32_e32 v73, v170, v73
	v_add_f32_e32 v73, v171, v73
	v_add_f32_e32 v73, v172, v73
	v_add_f32_e32 v73, v173, v73
	v_add_f32_e32 v73, v175, v73
	v_add_f32_e32 v73, v174, v73
	v_add_f32_e32 v73, v176, v73
	v_add_f32_e32 v73, v177, v73
	v_add_f32_e32 v73, v179, v73
	v_add_f32_e32 v73, v178, v73
	v_sub_f32_e32 v74, v195, v145
	v_add_f32_e32 v73, v180, v73
	v_exp_f32_e32 v74, v74
	v_sub_f32_e32 v75, v193, v145
	v_add_f32_e32 v73, v182, v73
	v_exp_f32_e32 v75, v75
	v_sub_f32_e32 v76, v194, v145
	v_add_f32_e32 v73, v183, v73
	v_exp_f32_e32 v76, v76
	v_sub_f32_e32 v77, v191, v145
	v_add_f32_e32 v73, v190, v73
	v_exp_f32_e32 v77, v77
	v_sub_f32_e32 v78, v192, v145
	v_add_f32_e32 v157, v157, v73
	v_exp_f32_e32 v78, v78
	v_sub_f32_e32 v79, v167, v145
	v_add_f32_e32 v73, v75, v74
	v_exp_f32_e32 v79, v79
	v_sub_f32_e32 v70, v70, v145
	v_add_f32_e32 v73, v76, v73
	v_exp_f32_e32 v167, v70
	v_sub_f32_e32 v69, v69, v145
	v_add_f32_e32 v70, v77, v73
	v_exp_f32_e32 v69, v69
	v_sub_f32_e32 v73, v196, v145
	v_add_f32_e32 v70, v78, v70
	v_exp_f32_e32 v168, v73
	v_sub_f32_e32 v71, v71, v145
	v_add_f32_e32 v70, v79, v70
	v_exp_f32_e32 v169, v71
	v_sub_f32_e32 v71, v72, v145
	v_add_f32_e32 v70, v167, v70
	v_exp_f32_e32 v170, v71
	v_add_f32_e32 v70, v69, v70
	v_add_f32_e32 v70, v168, v70
	v_add_f32_e32 v70, v169, v70
	v_sub_f32_e32 v64, v64, v145
	v_add_f32_e32 v171, v170, v70
	v_cvt_pk_bf16_f32 v70, v74, v75
	v_cvt_pk_bf16_f32 v71, v76, v77
	v_cvt_pk_bf16_f32 v72, v78, v79
	v_cvt_pk_bf16_f32 v73, v167, v69
	v_exp_f32_e32 v69, v64
	v_sub_f32_e32 v64, v66, v145
	v_mfma_f32_32x32x16_bf16 v[16:31], v[140:143], v[70:73], v[16:31]
	v_exp_f32_e32 v74, v64
	v_sub_f32_e32 v64, v67, v145
	v_exp_f32_e32 v75, v64
	v_sub_f32_e32 v64, v68, v145
	v_exp_f32_e32 v68, v64
	v_sub_f32_e32 v64, v65, v145
	v_cvt_pk_bf16_f32 v65, v170, v69
	v_mfma_f32_32x32x16_bf16 v[0:15], v[136:139], v[70:73], v[0:15]
	v_exp_f32_e32 v70, v64
	v_cvt_pk_bf16_f32 v64, v168, v169
	v_cvt_pk_bf16_f32 v66, v74, v75
	v_add_f32_e32 v69, v69, v171
	v_cvt_pk_bf16_f32 v67, v68, v70
	v_add_f32_e32 v69, v74, v69
	v_add_f32_e32 v69, v75, v69
	v_mfma_f32_32x32x16_bf16 v[16:31], v[132:135], v[64:67], v[16:31]
	v_add_f32_e32 v68, v68, v69
	v_add_f32_e32 v68, v70, v68
	v_add_f32_e32 v156, v156, v68
	s_cmp_eq_u32 s60, 9
	v_mfma_f32_32x32x16_bf16 v[0:15], v[128:131], v[64:67], v[0:15]
	s_cbranch_scc1 .LBB0_684
	v_mov_b32_e32 v167, v166
	s_branch .LBB0_678

; #define LAS __attribute__((address_space(3)))
; template <class MB, int V1, class VS> __device__ __forceinline__ void la_step(LA& st, const bf16x8 (&qf)[4], Frag& f, const char* kb, const VS& vs, const TP& t, const TP& n) {
;     f32x16 s = zero16();
; #pragma unroll
;     for (int d0 = 0; d0 < 4; ++d0) s = __builtin_amdgcn_mfma_f32_32x32x16_bf16(f.k[d0], qf[d0], s, 0, 0, 0);
;     la_loadK(f, kb, n);
;     float mx = NEGBIG;
; #pragma unroll
;     for (int r = 0; r < 16; ++r) { s[r] = MB::apply(t, r, s[r]); mx = __builtin_fmaxf(mx, s[r]); }
;     { auto rr = __builtin_amdgcn_permlane32_swap(__float_as_uint(mx), __float_as_uint(mx), false, false); mx = __builtin_fmaxf(__uint_as_float(rr[0]), __uint_as_float(rr[1])); }
;     if (__any(mx > st.m)) { const float mn = __builtin_fmaxf(st.m, mx), alpha = __builtin_amdgcn_exp2f(st.m - mn); st.m = mn; st.l *= alpha; st.o0 *= alpha; st.o1 *= alpha; }
;     float rs = 0.f;
; #pragma unroll
;     for (int r = 0; r < 16; ++r) { s[r] = __builtin_amdgcn_exp2f(s[r] - st.m); rs += s[r]; }
;     st.l += rs;
;     u32x4 p0, p1;
; #pragma unroll
;     for (int e = 0; e < 4; ++e) { p0[e] = cvt_pk_bf16(s[2 * e], s[2 * e + 1]); p1[e] = cvt_pk_bf16(s[8 + 2 * e], s[8 + 2 * e + 1]); }
;     const bf16x8 pf0 = __builtin_bit_cast(bf16x8, p0), pf1 = __builtin_bit_cast(bf16x8, p1);
;     st.o0 = __builtin_amdgcn_mfma_f32_32x32x16_bf16(f.v[0], pf0, st.o0, 0, 0, 0); st.o0 = __builtin_amdgcn_mfma_f32_32x32x16_bf16(f.v[1], pf1, st.o0, 0, 0, 0);
;     st.o1 = __builtin_amdgcn_mfma_f32_32x32x16_bf16(f.v[2], pf0, st.o1, 0, 0, 0); st.o1 = __builtin_amdgcn_mfma_f32_32x32x16_bf16(f.v[3], pf1, st.o1, 0, 0, 0);
;     vs.template load<V1>(f, n.voff);
; }
; __global__ void __launch_bounds__(NWAVES * 64, 2) mk_fwd(Args args) {
;     ...
;                 {   LA& st = sa; const bf16x8 (&qf)[4] = qa;
;                     auto tilx = [&](int i) -> TP { const int kr0 = rsa + 4 * i, t0 = 64 * kr0 + c0, tk = t0 + (lam & 7) + (lam >> 3) * 64; TP t;
;                         t.koff = ((unsigned)tk * PP + kc) * 2u; t.voff = (unsigned)(vt_off(vd, t0 + hi * 64) * 2);
;                         t.tp = (const LAS char*)(tabB + ((kr0 + hi - qrow + 7) * 128 + c0 - qc + 64)); t.cb = c0 - cs; t.tp2 = t.tp; return t; };
;                     LA_RUN(2, tilx, MB_BX, 512, PB, vs); }
.LBB0_685:
	v_or_b32_e32 v64, v64, v184
	v_lshl_or_b32 v64, v64, 7, s0
	v_add_lshl_u32 v64, v64, v164, 1
	v_ashrrev_i32_e32 v65, 31, v64
	v_lshl_add_u64 v[64:65], s[56:57], 0, v[64:65]
	v_add_co_u32_e32 v66, vcc, s80, v64
	v_add_u32_e32 v170, s24, v166
	s_nop 0
	v_addc_co_u32_e32 v67, vcc, 0, v65, vcc
	global_load_dwordx4 v[128:131], v[66:67], off offset:2560
	global_load_dwordx4 v[132:135], v[66:67], off offset:2048
	global_load_dwordx4 v[136:139], v[64:65], off offset:512
	global_load_dwordx4 v[140:143], v[64:65], off
	v_add_u32_e32 v167, 0x7120, v170
	s_waitcnt vmcnt(7)
	s_nop 0
	v_mfma_f32_32x32x16_bf16 v[64:79], v[112:115], v[96:99], 0
	s_waitcnt vmcnt(6)
	v_mfma_f32_32x32x16_bf16 v[64:79], v[120:123], v[100:103], v[64:79]
	s_waitcnt vmcnt(5)
	v_mfma_f32_32x32x16_bf16 v[64:79], v[116:119], v[104:107], v[64:79]
	s_waitcnt vmcnt(4)
	v_mfma_f32_32x32x16_bf16 v[64:79], v[124:127], v[108:111], v[64:79]
	global_load_dwordx4 v[112:115], v[152:153], off
	global_load_dwordx4 v[120:123], v[152:153], off offset:32
	global_load_dwordx4 v[116:119], v[152:153], off offset:64
	global_load_dwordx4 v[124:127], v[152:153], off offset:96
	ds_read2_b32 v[168:169], v167 offset1:1
	s_waitcnt lgkmcnt(0)
	s_nop 5
	v_add_f32_e32 v64, v64, v168
	v_cndmask_b32_e64 v167, v232, v64, s[6:7]
	v_add_f32_e32 v64, v65, v169
	v_add_u32_e32 v65, 0x7128, v170
	ds_read2_b32 v[168:169], v65 offset1:1
	v_cndmask_b32_e64 v64, v232, v64, s[8:9]
	v_max3_f32 v171, v167, s2, v64
	s_waitcnt lgkmcnt(0)
	v_add_f32_e32 v65, v66, v168
	v_cndmask_b32_e64 v66, v232, v65, s[10:11]
	v_add_f32_e32 v65, v67, v169
	v_add_u32_e32 v67, 0x7130, v170
	ds_read2_b32 v[168:169], v67 offset1:1
	v_cndmask_b32_e64 v65, v232, v65, s[12:13]
	v_max3_f32 v171, v171, v66, v65
	s_waitcnt lgkmcnt(0)
	v_add_f32_e32 v67, v68, v168
	v_cndmask_b32_e64 v68, v232, v67, s[14:15]
	v_add_f32_e32 v67, v69, v169
	v_add_u32_e32 v69, 0x7138, v170
	ds_read2_b32 v[168:169], v69 offset1:1
	v_cndmask_b32_e64 v67, v232, v67, s[16:17]
	v_max3_f32 v171, v171, v68, v67
	s_waitcnt lgkmcnt(0)
	v_add_f32_e32 v69, v70, v168
	v_cndmask_b32_e64 v70, v232, v69, s[18:19]
	v_add_f32_e32 v69, v71, v169
	v_add_u32_e32 v71, 0x7520, v170
	ds_read2_b32 v[168:169], v71 offset1:1
	v_cndmask_b32_e64 v69, v232, v69, s[20:21]
	v_max3_f32 v171, v171, v70, v69
	s_waitcnt lgkmcnt(0)
	v_add_f32_e32 v71, v72, v168
	v_cndmask_b32_e64 v72, v232, v71, s[6:7]
	v_add_f32_e32 v71, v73, v169
	v_add_u32_e32 v73, 0x7528, v170
	ds_read2_b32 v[168:169], v73 offset1:1
	v_cndmask_b32_e64 v71, v232, v71, s[8:9]
	v_max3_f32 v171, v171, v72, v71
	s_waitcnt lgkmcnt(0)
	v_add_f32_e32 v73, v74, v168
	v_cndmask_b32_e64 v74, v232, v73, s[10:11]
	v_add_f32_e32 v73, v75, v169
	v_add_u32_e32 v75, 0x7530, v170
	ds_read2_b32 v[168:169], v75 offset1:1
	v_cndmask_b32_e64 v73, v232, v73, s[12:13]
	v_max3_f32 v171, v171, v74, v73
	s_waitcnt lgkmcnt(0)
	v_add_f32_e32 v75, v76, v168
	v_cndmask_b32_e64 v76, v232, v75, s[14:15]
	v_add_f32_e32 v75, v77, v169
	v_add_u32_e32 v77, 0x7538, v170
	ds_read2_b32 v[168:169], v77 offset1:1
	v_cndmask_b32_e64 v75, v232, v75, s[16:17]
	v_max3_f32 v171, v171, v76, v75
	s_waitcnt lgkmcnt(0)
	v_add_f32_e32 v77, v78, v168
	v_cndmask_b32_e64 v78, v232, v77, s[18:19]
	v_add_f32_e32 v77, v79, v169
	v_cndmask_b32_e64 v77, v232, v77, s[20:21]
	v_max3_f32 v79, v171, v78, v77
	v_mov_b32_e32 v168, v79
	s_nop 1
	v_permlane32_swap_b32_e32 v79, v168
	v_max_f32_e32 v79, v79, v168
	v_cmp_gt_f32_e32 vcc, v79, v162
	s_cbranch_vccz .LBB0_687
	v_max_f32_e32 v79, v79, v79
	v_max_f32_e32 v168, v162, v162
	v_max_f32_e32 v79, v168, v79
	v_sub_f32_e32 v162, v162, v79
	v_exp_f32_e32 v162, v162
	s_nop 0
	v_mul_f32_e32 v157, v157, v162
	v_pk_mul_f32 v[62:63], v[62:63], v[162:163] op_sel_hi:[1,0]
	v_pk_mul_f32 v[60:61], v[60:61], v[162:163] op_sel_hi:[1,0]
	v_pk_mul_f32 v[58:59], v[58:59], v[162:163] op_sel_hi:[1,0]
	v_pk_mul_f32 v[56:57], v[56:57], v[162:163] op_sel_hi:[1,0]
	v_pk_mul_f32 v[54:55], v[54:55], v[162:163] op_sel_hi:[1,0]
	v_pk_mul_f32 v[52:53], v[52:53], v[162:163] op_sel_hi:[1,0]
	v_pk_mul_f32 v[50:51], v[50:51], v[162:163] op_sel_hi:[1,0]
	v_pk_mul_f32 v[48:49], v[48:49], v[162:163] op_sel_hi:[1,0]
	v_pk_mul_f32 v[46:47], v[46:47], v[162:163] op_sel_hi:[1,0]
	v_pk_mul_f32 v[44:45], v[44:45], v[162:163] op_sel_hi:[1,0]
	v_pk_mul_f32 v[42:43], v[42:43], v[162:163] op_sel_hi:[1,0]
	v_pk_mul_f32 v[40:41], v[40:41], v[162:163] op_sel_hi:[1,0]
	v_pk_mul_f32 v[38:39], v[38:39], v[162:163] op_sel_hi:[1,0]
	v_pk_mul_f32 v[36:37], v[36:37], v[162:163] op_sel_hi:[1,0]
	v_pk_mul_f32 v[34:35], v[34:35], v[162:163] op_sel_hi:[1,0]
	v_pk_mul_f32 v[32:33], v[32:33], v[162:163] op_sel_hi:[1,0]
	v_mov_b32_e32 v162, v79
.LBB0_687:
	v_sub_f32_e32 v65, v65, v162
	v_exp_f32_e32 v168, v65
	v_sub_f32_e32 v65, v68, v162
	v_exp_f32_e32 v169, v65
	v_sub_f32_e32 v65, v67, v162
	v_exp_f32_e32 v170, v65
	v_sub_f32_e32 v65, v70, v162
	v_sub_f32_e32 v79, v167, v162
	v_exp_f32_e32 v171, v65
	v_sub_f32_e32 v65, v69, v162
	v_exp_f32_e32 v79, v79
	v_sub_f32_e32 v64, v64, v162
	v_exp_f32_e32 v172, v65
	v_sub_f32_e32 v65, v72, v162
	v_exp_f32_e32 v64, v64
	v_sub_f32_e32 v66, v66, v162
	v_exp_f32_e32 v72, v65
	v_sub_f32_e32 v65, v71, v162
	v_exp_f32_e32 v66, v66
	v_exp_f32_e32 v173, v65
	v_sub_f32_e32 v65, v74, v162
	v_exp_f32_e32 v74, v65
	v_sub_f32_e32 v65, v73, v162
	v_exp_f32_e32 v73, v65
	v_sub_f32_e32 v65, v76, v162
	v_add_f32_e32 v167, v64, v79
	v_exp_f32_e32 v76, v65
	v_sub_f32_e32 v65, v75, v162
	v_add_f32_e32 v167, v66, v167
	v_exp_f32_e32 v75, v65
	v_cvt_pk_bf16_f32 v64, v79, v64
	v_cvt_pk_bf16_f32 v65, v66, v168
	v_cvt_pk_bf16_f32 v66, v169, v170
	v_cvt_pk_bf16_f32 v67, v171, v172
	v_sub_f32_e32 v68, v78, v162
	v_exp_f32_e32 v78, v68
	s_waitcnt vmcnt(4)
	v_mfma_f32_32x32x16_bf16 v[48:63], v[140:143], v[64:67], v[48:63]
	v_sub_f32_e32 v68, v77, v162
	v_add_f32_e32 v79, v168, v167
	v_exp_f32_e32 v77, v68
	v_add_f32_e32 v79, v169, v79
	v_add_f32_e32 v79, v170, v79
	v_add_f32_e32 v79, v171, v79
	v_add_f32_e32 v79, v172, v79
	v_mfma_f32_32x32x16_bf16 v[32:47], v[132:135], v[64:67], v[32:47]
	v_cvt_pk_bf16_f32 v68, v72, v173
	v_cvt_pk_bf16_f32 v69, v74, v73
	v_cvt_pk_bf16_f32 v70, v76, v75
	v_cvt_pk_bf16_f32 v71, v78, v77
	v_add_f32_e32 v72, v72, v79
	v_add_f32_e32 v72, v173, v72
	v_add_f32_e32 v64, v74, v72
	v_mfma_f32_32x32x16_bf16 v[48:63], v[136:139], v[68:71], v[48:63]
	v_add_f32_e32 v64, v73, v64
	v_add_f32_e32 v64, v76, v64
	v_add_f32_e32 v64, v75, v64
	v_add_f32_e32 v64, v78, v64
	s_xor_b64 s[26:27], s[22:23], -1
	v_add_f32_e32 v64, v77, v64
	v_add_f32_e32 v157, v157, v64
	v_mfma_f32_32x32x16_bf16 v[32:47], v[128:131], v[68:71], v[32:47]
	s_movk_i32 s24, 0x800
	s_mov_b64 s[22:23], 0
	s_and_b64 vcc, exec, s[26:27]
	s_cbranch_vccnz .LBB0_689
	v_mov_b32_e32 v64, v160
	s_branch .LBB0_685

; #define LAS __attribute__((address_space(3)))
; template <class MB, int V1, class VS> __device__ __forceinline__ void la_step(LA& st, const bf16x8 (&qf)[4], Frag& f, const char* kb, const VS& vs, const TP& t, const TP& n) {
;     f32x16 s = zero16();
; #pragma unroll
;     for (int d0 = 0; d0 < 4; ++d0) s = __builtin_amdgcn_mfma_f32_32x32x16_bf16(f.k[d0], qf[d0], s, 0, 0, 0);
;     la_loadK(f, kb, n);
;     float mx = NEGBIG;
; #pragma unroll
;     for (int r = 0; r < 16; ++r) { s[r] = MB::apply(t, r, s[r]); mx = __builtin_fmaxf(mx, s[r]); }
;     { auto rr = __builtin_amdgcn_permlane32_swap(__float_as_uint(mx), __float_as_uint(mx), false, false); mx = __builtin_fmaxf(__uint_as_float(rr[0]), __uint_as_float(rr[1])); }
;     if (__any(mx > st.m)) { const float mn = __builtin_fmaxf(st.m, mx), alpha = __builtin_amdgcn_exp2f(st.m - mn); st.m = mn; st.l *= alpha; st.o0 *= alpha; st.o1 *= alpha; }
;     float rs = 0.f;
; #pragma unroll
;     for (int r = 0; r < 16; ++r) { s[r] = __builtin_amdgcn_exp2f(s[r] - st.m); rs += s[r]; }
;     st.l += rs;
;     u32x4 p0, p1;
; #pragma unroll
;     for (int e = 0; e < 4; ++e) { p0[e] = cvt_pk_bf16(s[2 * e], s[2 * e + 1]); p1[e] = cvt_pk_bf16(s[8 + 2 * e], s[8 + 2 * e + 1]); }
;     const bf16x8 pf0 = __builtin_bit_cast(bf16x8, p0), pf1 = __builtin_bit_cast(bf16x8, p1);
;     st.o0 = __builtin_amdgcn_mfma_f32_32x32x16_bf16(f.v[0], pf0, st.o0, 0, 0, 0); st.o0 = __builtin_amdgcn_mfma_f32_32x32x16_bf16(f.v[1], pf1, st.o0, 0, 0, 0);
;     st.o1 = __builtin_amdgcn_mfma_f32_32x32x16_bf16(f.v[2], pf0, st.o1, 0, 0, 0); st.o1 = __builtin_amdgcn_mfma_f32_32x32x16_bf16(f.v[3], pf1, st.o1, 0, 0, 0);
;     vs.template load<V1>(f, n.voff);
; }
; __global__ void __launch_bounds__(NWAVES * 64, 2) mk_fwd(Args args) {
;     ...
;                 {   LA& st = sb; const bf16x8 (&qf)[4] = qb;
;                     auto tilx = [&](int i) -> TP { const int kr0 = rsb + 4 * i, t0 = 64 * kr0 + c0, tk = t0 + (lam & 7) + (lam >> 3) * 64; TP t;
;                         t.koff = ((unsigned)tk * PP + kc) * 2u; t.voff = (unsigned)(vt_off(vd, t0 + hi * 64) * 2);
;                         t.tp = (const LAS char*)(tabB + ((kr0 + hi - qrow - 1 + 7) * 128 + c0 - qc + 64)); t.cb = c0 - cs; t.tp2 = t.tp; return t; };
;                     LA_RUN(2, tilx, MB_BX, 512, PB, vs); }
.LBB0_690:
	v_add_u32_e32 v64, v159, v184
	v_lshl_or_b32 v64, v64, 7, s0
	v_add_lshl_u32 v64, v64, v164, 1
	v_ashrrev_i32_e32 v65, 31, v64
	v_lshl_add_u64 v[64:65], s[56:57], 0, v[64:65]
	v_add_co_u32_e32 v66, vcc, s80, v64
	v_add_u32_e32 v136, s24, v131
	s_nop 0
	v_addc_co_u32_e32 v67, vcc, 0, v65, vcc
	global_load_dwordx4 v[112:115], v[66:67], off offset:2560
	global_load_dwordx4 v[116:119], v[66:67], off offset:2048
	global_load_dwordx4 v[120:123], v[64:65], off offset:512
	global_load_dwordx4 v[124:127], v[64:65], off
	v_add_u32_e32 v132, 0x7120, v136
	s_waitcnt vmcnt(7)
	s_nop 0
	v_mfma_f32_32x32x16_bf16 v[64:79], v[96:99], v[80:83], 0
	s_waitcnt vmcnt(6)
	v_mfma_f32_32x32x16_bf16 v[64:79], v[104:107], v[84:87], v[64:79]
	s_waitcnt vmcnt(5)
	v_mfma_f32_32x32x16_bf16 v[64:79], v[100:103], v[88:91], v[64:79]
	s_waitcnt vmcnt(4)
	v_mfma_f32_32x32x16_bf16 v[64:79], v[108:111], v[92:95], v[64:79]
	global_load_dwordx4 v[96:99], v[128:129], off
	global_load_dwordx4 v[104:107], v[128:129], off offset:32
	global_load_dwordx4 v[100:103], v[128:129], off offset:64
	global_load_dwordx4 v[108:111], v[128:129], off offset:96
	ds_read2_b32 v[132:133], v132 offset1:1
	s_waitcnt lgkmcnt(0)
	s_nop 5
	v_add_f32_e32 v64, v64, v132
	v_cndmask_b32_e64 v132, v232, v64, s[6:7]
	v_add_f32_e32 v64, v65, v133
	v_add_u32_e32 v65, 0x7128, v136
	ds_read2_b32 v[134:135], v65 offset1:1
	v_cndmask_b32_e64 v64, v232, v64, s[8:9]
	v_max3_f32 v133, v132, s2, v64
	s_waitcnt lgkmcnt(0)
	v_add_f32_e32 v65, v66, v134
	v_cndmask_b32_e64 v66, v232, v65, s[10:11]
	v_add_f32_e32 v65, v67, v135
	v_add_u32_e32 v67, 0x7130, v136
	ds_read2_b32 v[134:135], v67 offset1:1
	v_cndmask_b32_e64 v65, v232, v65, s[12:13]
	v_max3_f32 v133, v133, v66, v65
	s_waitcnt lgkmcnt(0)
	v_add_f32_e32 v67, v68, v134
	v_cndmask_b32_e64 v68, v232, v67, s[14:15]
	v_add_f32_e32 v67, v69, v135
	v_add_u32_e32 v69, 0x7138, v136
	ds_read2_b32 v[134:135], v69 offset1:1
	v_cndmask_b32_e64 v67, v232, v67, s[16:17]
	v_max3_f32 v133, v133, v68, v67
	s_waitcnt lgkmcnt(0)
	v_add_f32_e32 v69, v70, v134
	v_cndmask_b32_e64 v70, v232, v69, s[18:19]
	v_add_f32_e32 v69, v71, v135
	v_add_u32_e32 v71, 0x7520, v136
	ds_read2_b32 v[134:135], v71 offset1:1
	v_cndmask_b32_e64 v69, v232, v69, s[20:21]
	v_max3_f32 v133, v133, v70, v69
	s_waitcnt lgkmcnt(0)
	v_add_f32_e32 v71, v72, v134
	v_cndmask_b32_e64 v72, v232, v71, s[6:7]
	v_add_f32_e32 v71, v73, v135
	v_add_u32_e32 v73, 0x7528, v136
	ds_read2_b32 v[134:135], v73 offset1:1
	v_cndmask_b32_e64 v71, v232, v71, s[8:9]
	v_max3_f32 v133, v133, v72, v71
	s_waitcnt lgkmcnt(0)
	v_add_f32_e32 v73, v74, v134
	v_cndmask_b32_e64 v74, v232, v73, s[10:11]
	v_add_f32_e32 v73, v75, v135
	v_add_u32_e32 v75, 0x7530, v136
	ds_read2_b32 v[134:135], v75 offset1:1
	v_cndmask_b32_e64 v73, v232, v73, s[12:13]
	v_max3_f32 v133, v133, v74, v73
	s_waitcnt lgkmcnt(0)
	v_add_f32_e32 v75, v76, v134
	v_cndmask_b32_e64 v76, v232, v75, s[14:15]
	v_add_f32_e32 v75, v77, v135
	v_add_u32_e32 v77, 0x7538, v136
	ds_read2_b32 v[134:135], v77 offset1:1
	v_cndmask_b32_e64 v75, v232, v75, s[16:17]
	v_max3_f32 v133, v133, v76, v75
	s_waitcnt lgkmcnt(0)
	v_add_f32_e32 v77, v78, v134
	v_cndmask_b32_e64 v78, v232, v77, s[18:19]
	v_add_f32_e32 v77, v79, v135
	v_cndmask_b32_e64 v77, v232, v77, s[20:21]
	v_max3_f32 v79, v133, v78, v77
	v_mov_b32_e32 v133, v79
	s_nop 1
	v_permlane32_swap_b32_e32 v79, v133
	v_max_f32_e32 v79, v79, v133
	v_cmp_gt_f32_e32 vcc, v79, v145
	s_cbranch_vccz .LBB0_692
	v_max_f32_e32 v79, v79, v79
	v_max_f32_e32 v133, v145, v145
	v_max_f32_e32 v79, v133, v79
	v_sub_f32_e32 v133, v145, v79
	v_exp_f32_e32 v134, v133
	v_mov_b32_e32 v145, v79
	v_mul_f32_e32 v156, v156, v134
	v_pk_mul_f32 v[30:31], v[30:31], v[134:135] op_sel_hi:[1,0]
	v_pk_mul_f32 v[28:29], v[28:29], v[134:135] op_sel_hi:[1,0]
	v_pk_mul_f32 v[26:27], v[26:27], v[134:135] op_sel_hi:[1,0]
	v_pk_mul_f32 v[24:25], v[24:25], v[134:135] op_sel_hi:[1,0]
	v_pk_mul_f32 v[22:23], v[22:23], v[134:135] op_sel_hi:[1,0]
	v_pk_mul_f32 v[20:21], v[20:21], v[134:135] op_sel_hi:[1,0]
	v_pk_mul_f32 v[18:19], v[18:19], v[134:135] op_sel_hi:[1,0]
	v_pk_mul_f32 v[16:17], v[16:17], v[134:135] op_sel_hi:[1,0]
	v_pk_mul_f32 v[14:15], v[14:15], v[134:135] op_sel_hi:[1,0]
	v_pk_mul_f32 v[12:13], v[12:13], v[134:135] op_sel_hi:[1,0]
	v_pk_mul_f32 v[10:11], v[10:11], v[134:135] op_sel_hi:[1,0]
	v_pk_mul_f32 v[8:9], v[8:9], v[134:135] op_sel_hi:[1,0]
	v_pk_mul_f32 v[6:7], v[6:7], v[134:135] op_sel_hi:[1,0]
	v_pk_mul_f32 v[4:5], v[4:5], v[134:135] op_sel_hi:[1,0]
	v_pk_mul_f32 v[2:3], v[2:3], v[134:135] op_sel_hi:[1,0]
	v_pk_mul_f32 v[0:1], v[0:1], v[134:135] op_sel_hi:[1,0]
.LBB0_692:
	v_sub_f32_e32 v65, v65, v145
	v_exp_f32_e32 v133, v65
	v_sub_f32_e32 v65, v68, v145
	v_exp_f32_e32 v134, v65
	v_sub_f32_e32 v65, v67, v145
	v_exp_f32_e32 v135, v65
	v_sub_f32_e32 v65, v70, v145
	v_sub_f32_e32 v79, v132, v145
	v_exp_f32_e32 v136, v65
	v_sub_f32_e32 v65, v69, v145
	v_exp_f32_e32 v79, v79
	v_sub_f32_e32 v64, v64, v145
	v_exp_f32_e32 v137, v65
	v_sub_f32_e32 v65, v72, v145
	v_exp_f32_e32 v64, v64
	v_sub_f32_e32 v66, v66, v145
	v_exp_f32_e32 v72, v65
	v_sub_f32_e32 v65, v71, v145
	v_exp_f32_e32 v66, v66
	v_exp_f32_e32 v138, v65
	v_sub_f32_e32 v65, v74, v145
	v_exp_f32_e32 v74, v65
	v_sub_f32_e32 v65, v73, v145
	v_exp_f32_e32 v73, v65
	v_sub_f32_e32 v65, v76, v145
	v_add_f32_e32 v132, v64, v79
	v_exp_f32_e32 v76, v65
	v_sub_f32_e32 v65, v75, v145
	v_add_f32_e32 v132, v66, v132
	v_exp_f32_e32 v75, v65
	v_cvt_pk_bf16_f32 v64, v79, v64
	v_cvt_pk_bf16_f32 v65, v66, v133
	v_cvt_pk_bf16_f32 v66, v134, v135
	v_cvt_pk_bf16_f32 v67, v136, v137
	v_sub_f32_e32 v68, v78, v145
	v_exp_f32_e32 v78, v68
	s_waitcnt vmcnt(4)
	v_mfma_f32_32x32x16_bf16 v[16:31], v[124:127], v[64:67], v[16:31]
	v_sub_f32_e32 v68, v77, v145
	v_add_f32_e32 v79, v133, v132
	v_exp_f32_e32 v77, v68
	v_add_f32_e32 v79, v134, v79
	v_add_f32_e32 v79, v135, v79
	v_add_f32_e32 v79, v136, v79
	v_add_f32_e32 v79, v137, v79
	v_mfma_f32_32x32x16_bf16 v[0:15], v[116:119], v[64:67], v[0:15]
	v_cvt_pk_bf16_f32 v68, v72, v138
	v_cvt_pk_bf16_f32 v69, v74, v73
	v_cvt_pk_bf16_f32 v70, v76, v75
	v_cvt_pk_bf16_f32 v71, v78, v77
	v_add_f32_e32 v72, v72, v79
	v_add_f32_e32 v72, v138, v72
	v_add_f32_e32 v64, v74, v72
	v_mfma_f32_32x32x16_bf16 v[16:31], v[120:123], v[68:71], v[16:31]
	v_add_f32_e32 v64, v73, v64
	v_add_f32_e32 v64, v76, v64
	v_add_f32_e32 v64, v75, v64
	v_add_f32_e32 v64, v78, v64
	s_xor_b64 s[26:27], s[22:23], -1
	v_add_f32_e32 v64, v77, v64
	v_add_f32_e32 v156, v156, v64
	v_mfma_f32_32x32x16_bf16 v[0:15], v[112:115], v[68:71], v[0:15]
	s_movk_i32 s24, 0x800
	s_mov_b64 s[22:23], 0
	s_and_b64 vcc, exec, s[26:27]
	s_cbranch_vccnz .LBB0_694
	v_mov_b32_e32 v159, v130
	s_branch .LBB0_690

; template <class MB, int V1, class VS> __device__ __forceinline__ void la_step(LA& st, const bf16x8 (&qf)[4], Frag& f, const char* kb, const VS& vs, const TP& t, const TP& n) {
;     f32x16 s = zero16();
; #pragma unroll
;     for (int d0 = 0; d0 < 4; ++d0) s = __builtin_amdgcn_mfma_f32_32x32x16_bf16(f.k[d0], qf[d0], s, 0, 0, 0);
;     la_loadK(f, kb, n);
;     float mx = NEGBIG;
; #pragma unroll
;     for (int r = 0; r < 16; ++r) { s[r] = MB::apply(t, r, s[r]); mx = __builtin_fmaxf(mx, s[r]); }
;     { auto rr = __builtin_amdgcn_permlane32_swap(__float_as_uint(mx), __float_as_uint(mx), false, false); mx = __builtin_fmaxf(__uint_as_float(rr[0]), __uint_as_float(rr[1])); }
;     if (__any(mx > st.m)) { const float mn = __builtin_fmaxf(st.m, mx), alpha = __builtin_amdgcn_exp2f(st.m - mn); st.m = mn; st.l *= alpha; st.o0 *= alpha; st.o1 *= alpha; }
;     float rs = 0.f;
; #pragma unroll
;     for (int r = 0; r < 16; ++r) { s[r] = __builtin_amdgcn_exp2f(s[r] - st.m); rs += s[r]; }
;     st.l += rs;
;     u32x4 p0, p1;
; #pragma unroll
;     for (int e = 0; e < 4; ++e) { p0[e] = cvt_pk_bf16(s[2 * e], s[2 * e + 1]); p1[e] = cvt_pk_bf16(s[8 + 2 * e], s[8 + 2 * e + 1]); }
;     const bf16x8 pf0 = __builtin_bit_cast(bf16x8, p0), pf1 = __builtin_bit_cast(bf16x8, p1);
;     st.o0 = __builtin_amdgcn_mfma_f32_32x32x16_bf16(f.v[0], pf0, st.o0, 0, 0, 0); st.o0 = __builtin_amdgcn_mfma_f32_32x32x16_bf16(f.v[1], pf1, st.o0, 0, 0, 0);
;     st.o1 = __builtin_amdgcn_mfma_f32_32x32x16_bf16(f.v[2], pf0, st.o1, 0, 0, 0); st.o1 = __builtin_amdgcn_mfma_f32_32x32x16_bf16(f.v[3], pf1, st.o1, 0, 0, 0);
;     vs.template load<V1>(f, n.voff);
; }
; __global__ void __launch_bounds__(NWAVES * 64, 2) mk_fwd(Args args) {
;     ...
;                 {
;                     LA& st = sa; const bf16x8 (&qf)[4] = qa;
;                     auto t16 = [&](int i) -> TP { const int sbr = s0 - 64 + 32 * i; const bool ok = sbr >= 0 && sbr < 1024; const int sb_ = ok ? sbr : s0;
;                         const int t0 = 16 * sb_ + cA, tk = t0 + (lam & 7) * 16 + (lam >> 3) * 128; TP t;
;                         t.koff = ((unsigned)tk * PP + kc) * 2u; t.voff = (unsigned)(vt_off(vd, cA * 1024 + sb_ + 8 * hi) * 2);
;                         t.tp = ok ? (const LAS char*)(tabD16 + (TABD_C + t0 + hi * 128 - tqa)) : negp; t.cb = 0; t.tp2 = t.tp; return t; };
;                     LA_RUN(5, t16, MB_D16, 32, PB, vs);
.LBB0_695:
	v_sub_f32_e32 v15, v114, v145
	v_exp_f32_e32 v15, v15
	v_sub_f32_e32 v0, v0, v145
	v_exp_f32_e32 v0, v0
	v_sub_f32_e32 v114, v115, v145
	v_exp_f32_e32 v114, v114
	v_sub_f32_e32 v2, v2, v145
	v_exp_f32_e32 v115, v2
	v_add_f32_e32 v2, v0, v15
	v_add_f32_e32 v2, v114, v2
	v_add_f32_e32 v116, v115, v2
	v_sub_f32_e32 v2, v4, v145
	v_exp_f32_e32 v117, v2
	v_sub_f32_e32 v2, v3, v145
	v_exp_f32_e32 v118, v2
	v_sub_f32_e32 v2, v6, v145
	v_exp_f32_e32 v119, v2
	v_sub_f32_e32 v2, v5, v145
	v_exp_f32_e32 v120, v2
	v_sub_f32_e32 v2, v8, v145
	v_exp_f32_e32 v121, v2
	v_sub_f32_e32 v2, v7, v145
	v_exp_f32_e32 v122, v2
	v_sub_f32_e32 v2, v10, v145
	v_exp_f32_e32 v10, v2
	v_sub_f32_e32 v2, v9, v145
	v_exp_f32_e32 v123, v2
	v_sub_f32_e32 v2, v12, v145
	v_exp_f32_e32 v12, v2
	v_sub_f32_e32 v2, v11, v145
	v_exp_f32_e32 v11, v2
	v_cvt_pk_bf16_f32 v2, v15, v0
	v_cvt_pk_bf16_f32 v3, v114, v115
	v_cvt_pk_bf16_f32 v4, v117, v118
	v_cvt_pk_bf16_f32 v5, v119, v120
	v_sub_f32_e32 v6, v14, v145
	v_exp_f32_e32 v0, v6
	s_waitcnt vmcnt(4)
	v_mfma_f32_32x32x16_bf16 v[32:47], v[76:79], v[2:5], v[32:47]
	v_sub_f32_e32 v6, v13, v145
	v_exp_f32_e32 v13, v6
	v_add_f32_e32 v14, v117, v116
	v_add_f32_e32 v14, v118, v14
	v_add_f32_e32 v14, v119, v14
	v_add_f32_e32 v14, v120, v14
	v_cvt_pk_bf16_f32 v6, v121, v122
	v_mfma_f32_32x32x16_bf16 v[16:31], v[68:71], v[2:5], v[16:31]
	v_cvt_pk_bf16_f32 v7, v10, v123
	v_cvt_pk_bf16_f32 v8, v12, v11
	v_cvt_pk_bf16_f32 v9, v0, v13
	v_add_f32_e32 v14, v121, v14
	v_add_f32_e32 v14, v122, v14
	v_add_f32_e32 v10, v10, v14
	v_add_f32_e32 v2, v123, v10
	v_mfma_f32_32x32x16_bf16 v[32:47], v[72:75], v[6:9], v[32:47]
	v_add_f32_e32 v2, v12, v2
	s_add_i32 s9, s9, s7
	v_add_f32_e32 v2, v11, v2
	s_lshl_b32 s9, s9, 1
	v_add_f32_e32 v0, v0, v2
	s_andn2_b32 s9, s9, 63
	v_add_f32_e32 v0, v13, v0
	v_mfma_f32_32x32x16_bf16 v[16:31], v[64:67], v[6:9], v[16:31]
	v_add_u32_e32 v1, s9, v155
	v_add_f32_e32 v158, v158, v0
	s_cmpk_eq_i32 s8, 0x60
	s_cbranch_scc1 .LBB0_698
.LBB0_696:
	v_lshlrev_b32_e32 v0, 1, v1
	v_ashrrev_i32_e32 v1, 31, v0
	v_lshl_add_u64 v[0:1], s[72:73], 0, v[0:1]
	v_add_co_u32_e32 v2, vcc, 0x100000, v0
	s_add_i32 s11, s1, s8
	s_nop 0
	v_addc_co_u32_e32 v3, vcc, 0, v1, vcc
	s_cmpk_lt_u32 s11, 0x400
	s_cselect_b64 vcc, -1, 0
	s_mov_b32 s10, s8
	s_and_b64 s[8:9], vcc, exec
	s_cselect_b32 s8, s11, s1
	global_load_dwordx4 v[64:67], v[2:3], off offset:2080
	global_load_dwordx4 v[68:71], v[2:3], off offset:2048
	global_load_dwordx4 v[72:75], v[0:1], off offset:32
	global_load_dwordx4 v[76:79], v[0:1], off
	v_lshl_add_u32 v0, s8, 6, v113
	s_add_i32 s8, s10, 32
	s_cmp_lg_u32 s10, 64
	s_cselect_b32 s9, s8, 64
	s_add_i32 s9, s9, s1
	s_cmpk_lt_u32 s9, 0x400
	v_add_u32_e32 v0, 0x4210, v0
	v_mov_b32_e32 v1, s53
	s_cselect_b32 s9, s9, s1
	v_cndmask_b32_e32 v118, v1, v0, vcc
	v_lshl_add_u32 v0, s9, 4, v112
	v_mul_lo_u32 v0, v0, s67
	v_add_lshl_u32 v114, v0, v181, 1
	s_nop 0
	s_waitcnt vmcnt(7)
	s_nop 0
	v_mfma_f32_32x32x16_bf16 v[0:15], v[60:63], v[80:83], 0
	s_waitcnt vmcnt(6)
	v_mfma_f32_32x32x16_bf16 v[0:15], v[56:59], v[88:91], v[0:15]
	s_waitcnt vmcnt(5)
	v_mfma_f32_32x32x16_bf16 v[0:15], v[52:55], v[96:99], v[0:15]
	s_waitcnt vmcnt(4)
	v_mfma_f32_32x32x16_bf16 v[0:15], v[48:51], v[104:107], v[0:15]
	global_load_dwordx4 v[60:63], v114, s[74:75]
	global_load_dwordx4 v[56:59], v114, s[74:75] offset:32
	global_load_dwordx4 v[52:55], v114, s[74:75] offset:64
	global_load_dwordx4 v[48:51], v114, s[74:75] offset:96
	ds_read2_b32 v[114:115], v118 offset1:16
	ds_read2_b32 v[116:117], v118 offset0:32 offset1:48
	s_waitcnt lgkmcnt(1)
	s_nop 4
	v_add_f32_e32 v114, v0, v114
	v_add_f32_e32 v0, v1, v115
	s_waitcnt lgkmcnt(0)
	v_add_f32_e32 v115, v2, v116
	v_add_f32_e32 v2, v3, v117
	ds_read2_b32 v[116:117], v118 offset0:64 offset1:80
	v_max3_f32 v1, v114, s2, v0
	v_max3_f32 v1, v1, v115, v2
	s_waitcnt lgkmcnt(0)
	v_add_f32_e32 v4, v4, v116
	v_add_f32_e32 v3, v5, v117
	ds_read2_b32 v[116:117], v118 offset0:96 offset1:112
	v_add_u32_e32 v118, 0x400, v118
	v_max3_f32 v1, v1, v4, v3
	s_waitcnt lgkmcnt(0)
	v_add_f32_e32 v6, v6, v116
	v_add_f32_e32 v5, v7, v117
	ds_read2_b32 v[116:117], v118 offset1:16
	v_max3_f32 v1, v1, v6, v5
	s_waitcnt lgkmcnt(0)
	v_add_f32_e32 v8, v8, v116
	v_add_f32_e32 v7, v9, v117
	ds_read2_b32 v[116:117], v118 offset0:32 offset1:48
	v_max3_f32 v1, v1, v8, v7
	s_waitcnt lgkmcnt(0)
	v_add_f32_e32 v10, v10, v116
	v_add_f32_e32 v9, v11, v117
	ds_read2_b32 v[116:117], v118 offset0:64 offset1:80
	v_max3_f32 v1, v1, v10, v9
	s_waitcnt lgkmcnt(0)
	v_add_f32_e32 v12, v12, v116
	v_add_f32_e32 v11, v13, v117
	ds_read2_b32 v[116:117], v118 offset0:96 offset1:112
	v_max3_f32 v1, v1, v12, v11
	s_waitcnt lgkmcnt(0)
	v_add_f32_e32 v14, v14, v116
	v_add_f32_e32 v13, v15, v117
	v_max3_f32 v1, v1, v14, v13
	v_mov_b32_e32 v15, v1
	s_nop 1
	v_permlane32_swap_b32_e32 v1, v15
	v_max_f32_e32 v1, v1, v15
	v_cmp_gt_f32_e32 vcc, v1, v145
	s_cbranch_vccz .LBB0_695
	v_max_f32_e32 v1, v1, v1
	v_max_f32_e32 v15, v145, v145
	v_max_f32_e32 v1, v15, v1
	v_sub_f32_e32 v15, v145, v1
	v_exp_f32_e32 v116, v15
	v_mov_b32_e32 v145, v1
	v_mul_f32_e32 v158, v158, v116
	v_pk_mul_f32 v[46:47], v[46:47], v[116:117] op_sel_hi:[1,0]
	v_pk_mul_f32 v[44:45], v[44:45], v[116:117] op_sel_hi:[1,0]
	v_pk_mul_f32 v[42:43], v[42:43], v[116:117] op_sel_hi:[1,0]
	v_pk_mul_f32 v[40:41], v[40:41], v[116:117] op_sel_hi:[1,0]
	v_pk_mul_f32 v[38:39], v[38:39], v[116:117] op_sel_hi:[1,0]
	v_pk_mul_f32 v[36:37], v[36:37], v[116:117] op_sel_hi:[1,0]
	v_pk_mul_f32 v[34:35], v[34:35], v[116:117] op_sel_hi:[1,0]
	v_pk_mul_f32 v[32:33], v[32:33], v[116:117] op_sel_hi:[1,0]
	v_pk_mul_f32 v[30:31], v[30:31], v[116:117] op_sel_hi:[1,0]
	v_pk_mul_f32 v[28:29], v[28:29], v[116:117] op_sel_hi:[1,0]
	v_pk_mul_f32 v[26:27], v[26:27], v[116:117] op_sel_hi:[1,0]
	v_pk_mul_f32 v[24:25], v[24:25], v[116:117] op_sel_hi:[1,0]
	v_pk_mul_f32 v[22:23], v[22:23], v[116:117] op_sel_hi:[1,0]
	v_pk_mul_f32 v[20:21], v[20:21], v[116:117] op_sel_hi:[1,0]
	v_pk_mul_f32 v[18:19], v[18:19], v[116:117] op_sel_hi:[1,0]
	v_pk_mul_f32 v[16:17], v[16:17], v[116:117] op_sel_hi:[1,0]
	s_branch .LBB0_695

; template <class MB, int V1, class VS> __device__ __forceinline__ void la_step(LA& st, const bf16x8 (&qf)[4], Frag& f, const char* kb, const VS& vs, const TP& t, const TP& n) {
;     f32x16 s = zero16();
; #pragma unroll
;     for (int d0 = 0; d0 < 4; ++d0) s = __builtin_amdgcn_mfma_f32_32x32x16_bf16(f.k[d0], qf[d0], s, 0, 0, 0);
;     la_loadK(f, kb, n);
;     float mx = NEGBIG;
; #pragma unroll
;     for (int r = 0; r < 16; ++r) { s[r] = MB::apply(t, r, s[r]); mx = __builtin_fmaxf(mx, s[r]); }
;     { auto rr = __builtin_amdgcn_permlane32_swap(__float_as_uint(mx), __float_as_uint(mx), false, false); mx = __builtin_fmaxf(__uint_as_float(rr[0]), __uint_as_float(rr[1])); }
;     if (__any(mx > st.m)) { const float mn = __builtin_fmaxf(st.m, mx), alpha = __builtin_amdgcn_exp2f(st.m - mn); st.m = mn; st.l *= alpha; st.o0 *= alpha; st.o1 *= alpha; }
;     float rs = 0.f;
; #pragma unroll
;     for (int r = 0; r < 16; ++r) { s[r] = __builtin_amdgcn_exp2f(s[r] - st.m); rs += s[r]; }
;     st.l += rs;
;     u32x4 p0, p1;
; #pragma unroll
;     for (int e = 0; e < 4; ++e) { p0[e] = cvt_pk_bf16(s[2 * e], s[2 * e + 1]); p1[e] = cvt_pk_bf16(s[8 + 2 * e], s[8 + 2 * e + 1]); }
;     const bf16x8 pf0 = __builtin_bit_cast(bf16x8, p0), pf1 = __builtin_bit_cast(bf16x8, p1);
;     st.o0 = __builtin_amdgcn_mfma_f32_32x32x16_bf16(f.v[0], pf0, st.o0, 0, 0, 0); st.o0 = __builtin_amdgcn_mfma_f32_32x32x16_bf16(f.v[1], pf1, st.o0, 0, 0, 0);
;     st.o1 = __builtin_amdgcn_mfma_f32_32x32x16_bf16(f.v[2], pf0, st.o1, 0, 0, 0); st.o1 = __builtin_amdgcn_mfma_f32_32x32x16_bf16(f.v[3], pf1, st.o1, 0, 0, 0);
;     vs.template load<V1>(f, n.voff);
; }
; __global__ void __launch_bounds__(NWAVES * 64, 2) mk_fwd(Args args) {
;     ...
;                 {
;                     LA& st = sb; const bf16x8 (&qf)[4] = qb;
;                     auto t16 = [&](int i) -> TP { const int sbr = s0 - 64 + 32 * i; const bool ok = sbr >= 0 && sbr < 1024; const int sb_ = ok ? sbr : s0;
;                         const int t0 = 16 * sb_ + cB, tk = t0 + (lam & 7) * 16 + (lam >> 3) * 128; TP t;
;                         t.koff = ((unsigned)tk * PP + kc) * 2u; t.voff = (unsigned)(vt_off(vd, cB * 1024 + sb_ + 8 * hi) * 2);
;                         t.tp = ok ? (const LAS char*)(tabD16 + (TABD_C + t0 + hi * 128 - tqb)) : negp; t.cb = 0; t.tp2 = t.tp; return t; };
;                     LA_RUN(5, t16, MB_D16, 32, PB, vs);
.LBB0_699:
	v_sub_f32_e32 v67, v67, v149
	v_sub_f32_e32 v162, v162, v149
	v_exp_f32_e32 v165, v67
	v_sub_f32_e32 v67, v70, v149
	v_exp_f32_e32 v162, v162
	v_sub_f32_e32 v64, v64, v149
	v_exp_f32_e32 v166, v67
	v_sub_f32_e32 v67, v69, v149
	v_exp_f32_e32 v64, v64
	v_sub_f32_e32 v66, v66, v149
	v_exp_f32_e32 v167, v67
	v_sub_f32_e32 v67, v72, v149
	v_exp_f32_e32 v66, v66
	v_sub_f32_e32 v65, v65, v149
	v_sub_f32_e32 v68, v68, v149
	v_exp_f32_e32 v72, v67
	v_sub_f32_e32 v67, v71, v149
	v_exp_f32_e32 v65, v65
	v_exp_f32_e32 v164, v68
	v_exp_f32_e32 v168, v67
	v_sub_f32_e32 v67, v74, v149
	v_exp_f32_e32 v74, v67
	v_sub_f32_e32 v67, v73, v149
	v_add_f32_e32 v163, v64, v162
	v_exp_f32_e32 v73, v67
	v_sub_f32_e32 v67, v76, v149
	v_add_f32_e32 v163, v66, v163
	v_exp_f32_e32 v76, v67
	v_sub_f32_e32 v67, v75, v149
	v_add_f32_e32 v163, v65, v163
	v_exp_f32_e32 v75, v67
	v_cvt_pk_bf16_f32 v64, v162, v64
	v_cvt_pk_bf16_f32 v65, v66, v65
	v_cvt_pk_bf16_f32 v66, v164, v165
	v_cvt_pk_bf16_f32 v67, v166, v167
	v_sub_f32_e32 v68, v78, v149
	v_exp_f32_e32 v78, v68
	s_waitcnt vmcnt(7)
	v_mfma_f32_32x32x16_bf16 v[48:63], v[140:143], v[64:67], v[48:63]
	v_sub_f32_e32 v68, v77, v149
	v_exp_f32_e32 v77, v68
	v_cvt_pk_bf16_f32 v68, v72, v168
	v_cvt_pk_bf16_f32 v69, v74, v73
	v_cvt_pk_bf16_f32 v70, v76, v75
	v_cvt_pk_bf16_f32 v71, v78, v77
	s_add_i32 s6, s6, s5
	s_waitcnt vmcnt(5)
	v_mfma_f32_32x32x16_bf16 v[0:15], v[132:135], v[64:67], v[0:15]
	s_lshl_b32 s6, s6, 1
	s_andn2_b32 s6, s6, 63
	v_add_u32_e32 v79, s6, v155
	s_cmpk_eq_i32 s4, 0x60
	v_mfma_f32_32x32x16_bf16 v[48:63], v[136:139], v[68:71], v[48:63]
	v_add_f32_e32 v136, v164, v163
	v_add_f32_e32 v136, v165, v136
	v_add_f32_e32 v136, v166, v136
	v_add_f32_e32 v136, v167, v136
	v_add_f32_e32 v72, v72, v136
	v_add_f32_e32 v72, v168, v72
	v_add_f32_e32 v72, v74, v72
	s_waitcnt vmcnt(4)
	v_mfma_f32_32x32x16_bf16 v[0:15], v[128:131], v[68:71], v[0:15]
	v_add_f32_e32 v64, v73, v72
	v_add_f32_e32 v64, v76, v64
	v_add_f32_e32 v64, v75, v64
	v_add_f32_e32 v64, v78, v64
	v_add_f32_e32 v64, v77, v64
	v_add_f32_e32 v156, v156, v64
	s_cbranch_scc1 .LBB0_702
.LBB0_700:
	v_lshlrev_b32_e32 v64, 1, v79
	v_ashrrev_i32_e32 v65, 31, v64
	v_lshl_add_u64 v[64:65], s[72:73], 0, v[64:65]
	s_mov_b32 s8, s4
	global_load_dwordx4 v[140:143], v[64:65], off
	global_load_dwordx4 v[136:139], v[64:65], off offset:32
	v_add_co_u32_e32 v64, vcc, s80, v64
	s_add_i32 s4, s1, s4
	s_nop 0
	v_addc_co_u32_e32 v65, vcc, 0, v65, vcc
	s_cmpk_lt_u32 s4, 0x400
	s_cselect_b64 vcc, -1, 0
	s_and_b64 s[6:7], vcc, exec
	s_cselect_b32 s4, s4, s1
	global_load_dwordx4 v[132:135], v[64:65], off offset:2048
	global_load_dwordx4 v[128:131], v[64:65], off offset:2080
	v_lshl_add_u32 v64, s4, 6, v161
	s_add_i32 s4, s8, 32
	s_cmp_lg_u32 s8, 64
	s_cselect_b32 s6, s4, 64
	s_add_i32 s6, s6, s1
	s_cmpk_lt_u32 s6, 0x400
	v_add_u32_e32 v64, 0x4210, v64
	v_mov_b32_e32 v65, s53
	s_cselect_b32 s6, s6, s1
	v_cndmask_b32_e32 v166, v65, v64, vcc
	v_lshl_add_u32 v64, s6, 4, v160
	v_mul_lo_u32 v64, v64, s67
	v_add_lshl_u32 v162, v64, v181, 1
	s_nop 0
	s_waitcnt vmcnt(7)
	s_nop 0
	v_mfma_f32_32x32x16_bf16 v[64:79], v[124:127], v[84:87], 0
	s_waitcnt vmcnt(6)
	v_mfma_f32_32x32x16_bf16 v[64:79], v[120:123], v[92:95], v[64:79]
	s_waitcnt vmcnt(5)
	v_mfma_f32_32x32x16_bf16 v[64:79], v[116:119], v[100:103], v[64:79]
	s_waitcnt vmcnt(4)
	v_mfma_f32_32x32x16_bf16 v[64:79], v[112:115], v[108:111], v[64:79]
	global_load_dwordx4 v[124:127], v162, s[74:75]
	global_load_dwordx4 v[120:123], v162, s[74:75] offset:32
	global_load_dwordx4 v[116:119], v162, s[74:75] offset:64
	global_load_dwordx4 v[112:115], v162, s[74:75] offset:96
	ds_read2_b32 v[162:163], v166 offset1:16
	ds_read2_b32 v[164:165], v166 offset0:32 offset1:48
	s_waitcnt lgkmcnt(1)
	s_nop 4
	v_add_f32_e32 v162, v64, v162
	v_add_f32_e32 v64, v65, v163
	s_waitcnt lgkmcnt(0)
	v_add_f32_e32 v66, v66, v164
	v_add_f32_e32 v65, v67, v165
	ds_read2_b32 v[164:165], v166 offset0:64 offset1:80
	v_max3_f32 v163, v162, s2, v64
	v_max3_f32 v163, v163, v66, v65
	s_waitcnt lgkmcnt(0)
	v_add_f32_e32 v68, v68, v164
	v_add_f32_e32 v67, v69, v165
	ds_read2_b32 v[164:165], v166 offset0:96 offset1:112
	v_add_u32_e32 v166, 0x400, v166
	v_max3_f32 v163, v163, v68, v67
	s_waitcnt lgkmcnt(0)
	v_add_f32_e32 v70, v70, v164
	v_add_f32_e32 v69, v71, v165
	ds_read2_b32 v[164:165], v166 offset1:16
	v_max3_f32 v163, v163, v70, v69
	s_waitcnt lgkmcnt(0)
	v_add_f32_e32 v72, v72, v164
	v_add_f32_e32 v71, v73, v165
	ds_read2_b32 v[164:165], v166 offset0:32 offset1:48
	v_max3_f32 v163, v163, v72, v71
	s_waitcnt lgkmcnt(0)
	v_add_f32_e32 v74, v74, v164
	v_add_f32_e32 v73, v75, v165
	ds_read2_b32 v[164:165], v166 offset0:64 offset1:80
	v_max3_f32 v163, v163, v74, v73
	s_waitcnt lgkmcnt(0)
	v_add_f32_e32 v76, v76, v164
	v_add_f32_e32 v75, v77, v165
	ds_read2_b32 v[164:165], v166 offset0:96 offset1:112
	v_max3_f32 v163, v163, v76, v75
	s_waitcnt lgkmcnt(0)
	v_add_f32_e32 v78, v78, v164
	v_add_f32_e32 v77, v79, v165
	v_max3_f32 v79, v163, v78, v77
	v_mov_b32_e32 v163, v79
	s_nop 1
	v_permlane32_swap_b32_e32 v79, v163
	v_max_f32_e32 v79, v79, v163
	v_cmp_gt_f32_e32 vcc, v79, v149
	s_cbranch_vccz .LBB0_699
	v_max_f32_e32 v79, v79, v79
	v_max_f32_e32 v163, v149, v149
	v_max_f32_e32 v79, v163, v79
	v_sub_f32_e32 v149, v149, v79
	v_exp_f32_e32 v164, v149
	v_mov_b32_e32 v149, v79
	v_mul_f32_e32 v156, v156, v164
	v_pk_mul_f32 v[62:63], v[62:63], v[164:165] op_sel_hi:[1,0]
	v_pk_mul_f32 v[60:61], v[60:61], v[164:165] op_sel_hi:[1,0]
	v_pk_mul_f32 v[58:59], v[58:59], v[164:165] op_sel_hi:[1,0]
	v_pk_mul_f32 v[56:57], v[56:57], v[164:165] op_sel_hi:[1,0]
	v_pk_mul_f32 v[54:55], v[54:55], v[164:165] op_sel_hi:[1,0]
	v_pk_mul_f32 v[52:53], v[52:53], v[164:165] op_sel_hi:[1,0]
	v_pk_mul_f32 v[50:51], v[50:51], v[164:165] op_sel_hi:[1,0]
	v_pk_mul_f32 v[48:49], v[48:49], v[164:165] op_sel_hi:[1,0]
	v_pk_mul_f32 v[14:15], v[14:15], v[164:165] op_sel_hi:[1,0]
	v_pk_mul_f32 v[12:13], v[12:13], v[164:165] op_sel_hi:[1,0]
	v_pk_mul_f32 v[10:11], v[10:11], v[164:165] op_sel_hi:[1,0]
	v_pk_mul_f32 v[8:9], v[8:9], v[164:165] op_sel_hi:[1,0]
	v_pk_mul_f32 v[6:7], v[6:7], v[164:165] op_sel_hi:[1,0]
	v_pk_mul_f32 v[4:5], v[4:5], v[164:165] op_sel_hi:[1,0]
	v_pk_mul_f32 v[2:3], v[2:3], v[164:165] op_sel_hi:[1,0]
	v_pk_mul_f32 v[0:1], v[0:1], v[164:165] op_sel_hi:[1,0]
	s_branch .LBB0_699

; #define LAS __attribute__((address_space(3)))
; __host__ __device__ __forceinline__ int vt_off(int d, int p) { return (d >> 1) * VTPP + (p >> 5) * 64 + (d & 1) * 32 + (p & 31); }
; __device__ __forceinline__ unsigned cvt_pk_bf16(float lo, float hi) { f32x2_c v = {lo, hi}; bf16x2_c b = __builtin_convertvector(v, bf16x2_c); return __builtin_bit_cast(unsigned, b); }
; #define LA_RUN2(NT, TILE, MB, V1, KB, VS_) do { Frag f_; { const TP t0_ = TILE(0); la_loadK(f_, KB, t0_); (VS_).template load<V1>(f_, t0_.voff); } \
;     _Pragma("unroll 1") for (int i_ = 0; i_ < (NT); ++i_) { const TP t_ = TILE(i_); const TP n_ = TILE(i_ + 1 < (NT) ? i_ + 1 : i_); la_step2<MB, V1>(sa, sb, qa, qb, f_, KB, VS_, t_, n_); } } while (0)
; template <class MB> __device__ __forceinline__ void la_soft(LA& st, f32x16& s, const TP& t, bf16x8& pf0, bf16x8& pf1) {
;     ...
;     float rs = 0.f;
; #pragma unroll
;     for (int r = 0; r < 16; ++r) { s[r] = __builtin_amdgcn_exp2f(s[r] - st.m); rs += s[r]; }
;     st.l += rs;
;     u32x4 p0, p1;
; #pragma unroll
;     for (int e = 0; e < 4; ++e) { p0[e] = cvt_pk_bf16(s[2 * e], s[2 * e + 1]); p1[e] = cvt_pk_bf16(s[8 + 2 * e], s[8 + 2 * e + 1]); }
;     pf0 = __builtin_bit_cast(bf16x8, p0); pf1 = __builtin_bit_cast(bf16x8, p1);
; }
; template <class MB, int V1, class VS> __device__ __forceinline__ void la_step2(LA& sa, LA& sb, const bf16x8 (&qa)[4], const bf16x8 (&qb)[4], Frag& f, const char* kb, const VS& vs, const TP& t, const TP& n) {
;     bf16x8 pa0, pa1;
;     { f32x16 s0 = zero16();
; #pragma unroll
;       for (int d0 = 0; d0 < 4; ++d0) s0 = __builtin_amdgcn_mfma_f32_32x32x16_bf16(f.k[d0], qa[d0], s0, 0, 0, 0);
;       la_soft<MB>(sa, s0, t, pa0, pa1); }
; __global__ void __launch_bounds__(NWAVES * 64, 2) mk_fwd(Args args) {
;     ...
;                 auto t4 = [&](int i) -> TP { const int cq = (cA & 3) + 4 * (i >> 1), sb_ = s0 - 16 + 32 * (i & 1);
;                     const int t0 = 16 * sb_ + cq; int tk = t0 + (lam & 7) * 16 + (lam >> 3) * 128; tk = tk < 0 ? 0 : (tk > SEQ - 1 ? SEQ - 1 : tk); TP t;
;                     t.koff = ((unsigned)tk * PP + kc) * 2u; t.voff = (unsigned)(vt_off(vd, cq * 1024 + sb_ + 8 * hi) * 2);
;                     t.tp = (const LAS char*)(tabD4 + (1024 + t0 + hi * 128 - tqa)); t.tp2 = t.tp - 16; t.cb = (sb_ < 0 ? 1 : 0) | (sb_ + 32 > 1024 ? 2 : 0); return t; };
;                 LA_RUN2(8, t4, MB_D4M, 96, PB, vs);
.LBB0_703:
	v_add_f32_e32 v76, v161, v160
	v_add_f32_e32 v76, v162, v76
	v_add_f32_e32 v76, v163, v76
	v_add_f32_e32 v76, v164, v76
	v_add_f32_e32 v76, v165, v76
	v_add_f32_e32 v76, v167, v76
	v_add_f32_e32 v76, v166, v76
	v_add_f32_e32 v76, v168, v76
	v_add_f32_e32 v76, v169, v76
	v_add_f32_e32 v76, v171, v76
	v_add_f32_e32 v76, v170, v76
	v_add_f32_e32 v76, v172, v76
	v_add_f32_e32 v76, v173, v76
	v_add_f32_e32 v76, v174, v76
	v_add_f32_e32 v76, v175, v76
	v_add_f32_e32 v158, v158, v76
	v_sub_f32_e32 v76, v176, v149
	v_exp_f32_e32 v76, v76
	v_sub_f32_e32 v64, v64, v149
	v_exp_f32_e32 v77, v64
	v_sub_f32_e32 v79, v178, v149
	v_exp_f32_e32 v79, v79
	v_sub_f32_e32 v159, v177, v149
	v_exp_f32_e32 v159, v159
	v_sub_f32_e32 v155, v155, v149
	v_exp_f32_e32 v155, v155
	v_sub_f32_e32 v68, v68, v149
	v_add_f32_e32 v78, v77, v76
	v_exp_f32_e32 v160, v68
	v_sub_f32_e32 v70, v70, v149
	v_add_f32_e32 v68, v79, v78
	v_exp_f32_e32 v78, v70
	v_sub_f32_e32 v69, v69, v149
	v_add_f32_e32 v68, v159, v68
	v_exp_f32_e32 v161, v69
	v_sub_f32_e32 v69, v72, v149
	v_add_f32_e32 v68, v155, v68
	v_exp_f32_e32 v72, v69
	v_sub_f32_e32 v69, v71, v149
	v_add_f32_e32 v68, v160, v68
	v_exp_f32_e32 v162, v69
	v_add_f32_e32 v68, v78, v68
	v_add_f32_e32 v68, v161, v68
	v_add_f32_e32 v68, v72, v68
	v_add_f32_e32 v163, v162, v68
	v_sub_f32_e32 v68, v74, v149
	v_exp_f32_e32 v74, v68
	v_sub_f32_e32 v68, v73, v149
	v_exp_f32_e32 v73, v68
	v_sub_f32_e32 v68, v75, v149
	v_exp_f32_e32 v75, v68
	v_cvt_pk_bf16_f32 v68, v76, v77
	v_cvt_pk_bf16_f32 v69, v79, v159
	v_cvt_pk_bf16_f32 v70, v155, v160
	v_cvt_pk_bf16_f32 v71, v78, v161
	v_sub_f32_e32 v67, v67, v149
	v_sub_f32_e32 v66, v66, v149
	v_mfma_f32_32x32x16_bf16 v[48:63], v[140:143], v[68:71], v[48:63]
	v_sub_f32_e32 v65, v65, v149
	v_exp_f32_e32 v76, v67
	v_exp_f32_e32 v65, v65
	v_add_f32_e32 v67, v74, v163
	v_add_f32_e32 v67, v73, v67
	v_add_f32_e32 v67, v75, v67
	v_add_f32_e32 v77, v76, v67
	v_mfma_f32_32x32x16_bf16 v[0:15], v[136:139], v[68:71], v[0:15]
	v_exp_f32_e32 v70, v66
	v_cvt_pk_bf16_f32 v66, v72, v162
	v_cvt_pk_bf16_f32 v67, v74, v73
	v_cvt_pk_bf16_f32 v68, v75, v76
	v_cvt_pk_bf16_f32 v69, v70, v65
	s_lshl_b32 s4, s11, 11
	s_lshl_b32 s5, s12, 1
	v_mfma_f32_32x32x16_bf16 v[48:63], v[132:135], v[66:69], v[48:63]
	s_add_i32 s4, s5, s4
	v_add_f32_e32 v70, v70, v77
	s_andn2_b32 s4, s4, 63
	v_add_f32_e32 v65, v65, v70
	s_add_i32 s10, s10, 32
	s_add_i32 s9, s9, 1
	s_add_i32 s8, s8, 2
	v_mfma_f32_32x32x16_bf16 v[0:15], v[128:131], v[66:69], v[0:15]
	v_add_u32_e32 v64, s4, v146
	v_add_f32_e32 v156, v156, v65
	s_cmpk_eq_i32 s10, 0x100
	s_cbranch_scc1 .LBB0_708
.LBB0_704:
	v_or_b32_e32 v64, v64, v147
	v_lshlrev_b32_e32 v64, 1, v64
	v_ashrrev_i32_e32 v65, 31, v64
	v_lshl_add_u64 v[64:65], s[72:73], 0, v[64:65]
	global_load_dwordx4 v[140:143], v[64:65], off
	global_load_dwordx4 v[132:135], v[64:65], off offset:96
	v_add_co_u32_e32 v64, vcc, s80, v64
	s_and_b32 s5, s10, 32
	s_nop 0
	v_addc_co_u32_e32 v65, vcc, 0, v65, vcc
	s_and_b32 s4, s8, 12
	s_add_i32 s6, s1, s5
	global_load_dwordx4 v[136:139], v[64:65], off offset:2048
	global_load_dwordx4 v[128:131], v[64:65], off offset:2144
	v_lshl_add_u32 v64, s4, 2, v154
	s_lshl_b32 s4, s6, 6
	v_add_u32_e32 v159, s4, v64
	v_add_u32_e32 v155, 0x1800, v159
	ds_read2_b32 v[160:161], v155 offset0:128 offset1:144
	s_cmpk_lt_i32 s6, 0x3e1
	s_waitcnt vmcnt(7)
	v_mfma_f32_32x32x16_bf16 v[64:79], v[124:127], v[80:83], 0
	s_cselect_b64 s[4:5], -1, 0
	s_cmp_gt_i32 s6, -1
	s_cselect_b64 s[6:7], -1, 0
	v_add_u32_e32 v159, 0x1c00, v159
	s_waitcnt vmcnt(6)
	v_mfma_f32_32x32x16_bf16 v[64:79], v[120:123], v[88:91], v[64:79]
	s_waitcnt vmcnt(5)
	v_mfma_f32_32x32x16_bf16 v[64:79], v[116:119], v[96:99], v[64:79]
	s_waitcnt vmcnt(4)
	v_mfma_f32_32x32x16_bf16 v[64:79], v[112:115], v[104:107], v[64:79]
	s_waitcnt lgkmcnt(0)
	s_nop 10
	v_add_f32_e32 v64, v64, v160
	v_cndmask_b32_e64 v160, v232, v64, s[6:7]
	v_add_f32_e32 v64, v65, v161
	v_cndmask_b32_e64 v161, v232, v64, s[6:7]
	ds_read2_b32 v[64:65], v155 offset0:160 offset1:176
	v_max3_f32 v164, v160, s2, v161
	s_waitcnt lgkmcnt(0)
	v_add_f32_e32 v64, v66, v64
	v_cndmask_b32_e64 v162, v232, v64, s[6:7]
	v_add_f32_e32 v64, v67, v65
	v_cndmask_b32_e64 v163, v232, v64, s[6:7]
	ds_read2_b32 v[64:65], v155 offset0:192 offset1:208
	v_max3_f32 v66, v164, v162, v163
	s_waitcnt lgkmcnt(0)
	v_add_f32_e32 v64, v68, v64
	v_cndmask_b32_e64 v164, v232, v64, s[6:7]
	v_add_f32_e32 v64, v69, v65
	v_cndmask_b32_e64 v165, v232, v64, s[6:7]
	ds_read2_b32 v[64:65], v155 offset0:224 offset1:240
	v_max3_f32 v66, v66, v164, v165
	s_waitcnt lgkmcnt(0)
	v_add_f32_e32 v64, v70, v64
	v_cndmask_b32_e64 v167, v232, v64, s[6:7]
	v_add_f32_e32 v64, v71, v65
	v_cndmask_b32_e64 v166, v232, v64, s[6:7]
	ds_read2_b32 v[64:65], v159 offset0:128 offset1:144
	v_max3_f32 v66, v66, v167, v166
	s_waitcnt lgkmcnt(0)
	v_add_f32_e32 v64, v72, v64
	v_cndmask_b32_e64 v168, v232, v64, s[4:5]
	v_add_f32_e32 v64, v73, v65
	v_cndmask_b32_e64 v169, v232, v64, s[4:5]
	ds_read2_b32 v[64:65], v159 offset0:160 offset1:176
	v_max3_f32 v66, v66, v168, v169
	s_waitcnt lgkmcnt(0)
	v_add_f32_e32 v64, v74, v64
	v_cndmask_b32_e64 v171, v232, v64, s[4:5]
	v_add_f32_e32 v64, v75, v65
	v_cndmask_b32_e64 v170, v232, v64, s[4:5]
	ds_read2_b32 v[64:65], v159 offset0:192 offset1:208
	v_max3_f32 v66, v66, v171, v170
	s_waitcnt lgkmcnt(0)
	v_add_f32_e32 v64, v76, v64
	v_cndmask_b32_e64 v172, v232, v64, s[4:5]
	v_add_f32_e32 v64, v77, v65
	v_cndmask_b32_e64 v173, v232, v64, s[4:5]
	ds_read2_b32 v[64:65], v159 offset0:224 offset1:240
	v_max3_f32 v66, v66, v172, v173
	s_waitcnt lgkmcnt(0)
	v_add_f32_e32 v64, v78, v64
	v_cndmask_b32_e64 v174, v232, v64, s[4:5]
	v_add_f32_e32 v64, v79, v65
	v_cndmask_b32_e64 v175, v232, v64, s[4:5]
	v_max3_f32 v64, v66, v174, v175
	v_mov_b32_e32 v65, v64
	s_nop 1
	v_permlane32_swap_b32_e32 v64, v65
	v_max_f32_e32 v64, v64, v65
	v_cmp_gt_f32_e32 vcc, v64, v145
	s_cbranch_vccz .LBB0_706
; #define LAS __attribute__((address_space(3)))
; __host__ __device__ __forceinline__ int vt_off(int d, int p) { return (d >> 1) * VTPP + (p >> 5) * 64 + (d & 1) * 32 + (p & 31); }
; template <class MB, int V1, class VS> __device__ __forceinline__ void la_step2(LA& sa, LA& sb, const bf16x8 (&qa)[4], const bf16x8 (&qb)[4], Frag& f, const char* kb, const VS& vs, const TP& t, const TP& n) {
;     ...
;     f32x16 s1 = zero16();
; #pragma unroll
;     for (int d0 = 0; d0 < 4; ++d0) s1 = __builtin_amdgcn_mfma_f32_32x32x16_bf16(f.k[d0], qb[d0], s1, 0, 0, 0);
;     la_loadK(f, kb, n);
;     sa.o0 = __builtin_amdgcn_mfma_f32_32x32x16_bf16(f.v[0], pa0, sa.o0, 0, 0, 0); sa.o1 = __builtin_amdgcn_mfma_f32_32x32x16_bf16(f.v[2], pa0, sa.o1, 0, 0, 0);
;     sa.o0 = __builtin_amdgcn_mfma_f32_32x32x16_bf16(f.v[1], pa1, sa.o0, 0, 0, 0); sa.o1 = __builtin_amdgcn_mfma_f32_32x32x16_bf16(f.v[3], pa1, sa.o1, 0, 0, 0);
;     { bf16x8 pb0, pb1; const TP tb = MB::second(t);
;       la_soft<MB>(sb, s1, tb, pb0, pb1);
;       sb.o0 = __builtin_amdgcn_mfma_f32_32x32x16_bf16(f.v[0], pb0, sb.o0, 0, 0, 0); sb.o1 = __builtin_amdgcn_mfma_f32_32x32x16_bf16(f.v[2], pb0, sb.o1, 0, 0, 0);
;       sb.o0 = __builtin_amdgcn_mfma_f32_32x32x16_bf16(f.v[1], pb1, sb.o0, 0, 0, 0); sb.o1 = __builtin_amdgcn_mfma_f32_32x32x16_bf16(f.v[3], pb1, sb.o1, 0, 0, 0); }
; __global__ void __launch_bounds__(NWAVES * 64, 2) mk_fwd(Args args) {
;     ...
;                 auto t4 = [&](int i) -> TP { const int cq = (cA & 3) + 4 * (i >> 1), sb_ = s0 - 16 + 32 * (i & 1);
;                     const int t0 = 16 * sb_ + cq; int tk = t0 + (lam & 7) * 16 + (lam >> 3) * 128; tk = tk < 0 ? 0 : (tk > SEQ - 1 ? SEQ - 1 : tk); TP t;
;                     t.koff = ((unsigned)tk * PP + kc) * 2u; t.voff = (unsigned)(vt_off(vd, cq * 1024 + sb_ + 8 * hi) * 2);
;                     t.tp = (const LAS char*)(tabD4 + (1024 + t0 + hi * 128 - tqa)); t.tp2 = t.tp - 16; t.cb = (sb_ < 0 ? 1 : 0) | (sb_ + 32 > 1024 ? 2 : 0); return t; };
	v_max_f32_e32 v64, v64, v64
	v_max_f32_e32 v65, v145, v145
	v_max_f32_e32 v65, v65, v64
	v_sub_f32_e32 v64, v145, v65
	v_exp_f32_e32 v64, v64
	v_mov_b32_e32 v145, v65
	v_mul_f32_e32 v158, v158, v64
	v_pk_mul_f32 v[46:47], v[46:47], v[64:65] op_sel_hi:[1,0]
	v_pk_mul_f32 v[44:45], v[44:45], v[64:65] op_sel_hi:[1,0]
	v_pk_mul_f32 v[42:43], v[42:43], v[64:65] op_sel_hi:[1,0]
	v_pk_mul_f32 v[40:41], v[40:41], v[64:65] op_sel_hi:[1,0]
	v_pk_mul_f32 v[38:39], v[38:39], v[64:65] op_sel_hi:[1,0]
	v_pk_mul_f32 v[36:37], v[36:37], v[64:65] op_sel_hi:[1,0]
	v_pk_mul_f32 v[34:35], v[34:35], v[64:65] op_sel_hi:[1,0]
	v_pk_mul_f32 v[32:33], v[32:33], v[64:65] op_sel_hi:[1,0]
	v_pk_mul_f32 v[30:31], v[30:31], v[64:65] op_sel_hi:[1,0]
	v_pk_mul_f32 v[28:29], v[28:29], v[64:65] op_sel_hi:[1,0]
	v_pk_mul_f32 v[26:27], v[26:27], v[64:65] op_sel_hi:[1,0]
	v_pk_mul_f32 v[24:25], v[24:25], v[64:65] op_sel_hi:[1,0]
	v_pk_mul_f32 v[22:23], v[22:23], v[64:65] op_sel_hi:[1,0]
	v_pk_mul_f32 v[20:21], v[20:21], v[64:65] op_sel_hi:[1,0]
	v_pk_mul_f32 v[18:19], v[18:19], v[64:65] op_sel_hi:[1,0]
	v_pk_mul_f32 v[16:17], v[16:17], v[64:65] op_sel_hi:[1,0]
.LBB0_706:
	s_cmpk_lg_i32 s10, 0xe0
	s_cselect_b32 s12, s9, 7
	s_lshl_b32 s11, s12, 1
	s_lshl_b32 s12, s12, 5
	s_and_b32 s12, s12, 32
	s_and_b32 s11, s11, 28
	s_add_i32 s12, s1, s12
	s_or_b32 s11, s11, s0
	s_lshl_b32 s13, s12, 4
	s_add_i32 s13, s13, s11
	v_add_u32_e32 v64, s13, v157
	v_med3_i32 v64, v64, 0, v254
	v_mul_u32_u24_e32 v64, 0x1a40, v64
	v_add_lshl_u32 v180, v64, v181, 1
	s_nop 0
	s_nop 1
	v_mfma_f32_32x32x16_bf16 v[64:79], v[124:127], v[84:87], 0
	v_sub_f32_e32 v124, v160, v145
	v_exp_f32_e32 v160, v124
	v_sub_f32_e32 v124, v161, v145
	v_exp_f32_e32 v161, v124
	v_sub_f32_e32 v124, v162, v145
	v_exp_f32_e32 v162, v124
	v_sub_f32_e32 v124, v163, v145
	v_mfma_f32_32x32x16_bf16 v[64:79], v[120:123], v[92:95], v[64:79]
	v_sub_f32_e32 v120, v164, v145
	v_exp_f32_e32 v164, v120
	v_sub_f32_e32 v120, v165, v145
	v_exp_f32_e32 v165, v120
	v_sub_f32_e32 v120, v167, v145
	v_exp_f32_e32 v163, v124
	v_exp_f32_e32 v167, v120
	v_mfma_f32_32x32x16_bf16 v[64:79], v[116:119], v[100:103], v[64:79]
	v_sub_f32_e32 v116, v166, v145
	v_exp_f32_e32 v166, v116
	v_sub_f32_e32 v116, v168, v145
	v_exp_f32_e32 v168, v116
	v_sub_f32_e32 v116, v169, v145
	v_exp_f32_e32 v169, v116
	v_sub_f32_e32 v116, v171, v145
	v_exp_f32_e32 v171, v116
	v_sub_f32_e32 v116, v172, v145
	v_exp_f32_e32 v172, v116
	v_sub_f32_e32 v116, v173, v145
	v_mfma_f32_32x32x16_bf16 v[64:79], v[112:115], v[108:111], v[64:79]
	v_sub_f32_e32 v112, v170, v145
	v_exp_f32_e32 v173, v116
	v_sub_f32_e32 v116, v174, v145
	v_exp_f32_e32 v170, v112
	v_cvt_pk_bf16_f32 v112, v160, v161
	v_cvt_pk_bf16_f32 v113, v162, v163
	v_cvt_pk_bf16_f32 v114, v164, v165
	v_cvt_pk_bf16_f32 v115, v167, v166
	v_exp_f32_e32 v174, v116
	v_sub_f32_e32 v116, v175, v145
	s_waitcnt vmcnt(3)
	v_mfma_f32_32x32x16_bf16 v[32:47], v[140:143], v[112:115], v[32:47]
	v_exp_f32_e32 v175, v116
	global_load_dwordx4 v[124:127], v180, s[74:75]
	global_load_dwordx4 v[120:123], v180, s[74:75] offset:32
	v_cvt_pk_bf16_f32 v176, v168, v169
	v_cvt_pk_bf16_f32 v177, v171, v170
	v_cvt_pk_bf16_f32 v178, v172, v173
	v_cvt_pk_bf16_f32 v179, v174, v175
	s_waitcnt vmcnt(3)
	v_mfma_f32_32x32x16_bf16 v[16:31], v[136:139], v[112:115], v[16:31]
	global_load_dwordx4 v[116:119], v180, s[74:75] offset:64
	global_load_dwordx4 v[112:115], v180, s[74:75] offset:96
	ds_read2_b32 v[182:183], v155 offset0:124 offset1:140
	ds_read2_b32 v[184:185], v159 offset0:220 offset1:236
	s_waitcnt lgkmcnt(1)
	v_add_f32_e32 v64, v64, v182
	v_mfma_f32_32x32x16_bf16 v[32:47], v[132:135], v[176:179], v[32:47]
	s_waitcnt vmcnt(4)
	v_mfma_f32_32x32x16_bf16 v[16:31], v[128:131], v[176:179], v[16:31]
	ds_read2_b32 v[178:179], v155 offset0:156 offset1:172
	v_cndmask_b32_e64 v176, v232, v64, s[6:7]
	v_add_f32_e32 v64, v65, v183
	ds_read2_b32 v[182:183], v155 offset0:188 offset1:204
	v_cndmask_b32_e64 v64, v232, v64, s[6:7]
	s_waitcnt lgkmcnt(1)
	v_add_f32_e32 v66, v66, v178
	v_cndmask_b32_e64 v178, v232, v66, s[6:7]
	v_add_f32_e32 v66, v67, v179
	v_cndmask_b32_e64 v177, v232, v66, s[6:7]
	ds_read2_b32 v[66:67], v155 offset0:220 offset1:236
	s_waitcnt lgkmcnt(1)
	v_add_f32_e32 v68, v68, v182
	v_cndmask_b32_e64 v155, v232, v68, s[6:7]
	v_add_f32_e32 v68, v69, v183
	ds_read2_b32 v[182:183], v159 offset0:124 offset1:140
	s_waitcnt lgkmcnt(1)
	v_add_f32_e32 v66, v70, v66
	v_cndmask_b32_e64 v70, v232, v66, s[6:7]
	v_add_f32_e32 v66, v71, v67
	v_cndmask_b32_e64 v69, v232, v66, s[6:7]
	ds_read2_b32 v[66:67], v159 offset0:156 offset1:172
	s_waitcnt lgkmcnt(1)
	v_add_f32_e32 v71, v72, v182
	v_cndmask_b32_e64 v72, v232, v71, s[4:5]
	v_add_f32_e32 v71, v73, v183
	ds_read2_b32 v[182:183], v159 offset0:188 offset1:204
	v_max3_f32 v65, v176, s2, v64
	v_max3_f32 v65, v65, v178, v177
	v_cndmask_b32_e64 v68, v232, v68, s[6:7]
	s_waitcnt lgkmcnt(1)
	v_add_f32_e32 v66, v74, v66
	v_max3_f32 v65, v65, v155, v68
	v_cndmask_b32_e64 v74, v232, v66, s[4:5]
	v_add_f32_e32 v66, v75, v67
	v_max3_f32 v65, v65, v70, v69
	v_cndmask_b32_e64 v71, v232, v71, s[4:5]
	v_cndmask_b32_e64 v73, v232, v66, s[4:5]
	s_waitcnt lgkmcnt(0)
	v_add_f32_e32 v66, v76, v182
	v_max3_f32 v65, v65, v72, v71
	v_cndmask_b32_e64 v75, v232, v66, s[4:5]
	v_add_f32_e32 v66, v77, v183
	v_max3_f32 v65, v65, v74, v73
	v_cndmask_b32_e64 v67, v232, v66, s[4:5]
	v_max3_f32 v76, v65, v75, v67
	v_add_f32_e32 v65, v78, v184
	v_cndmask_b32_e64 v66, v232, v65, s[4:5]
	v_add_f32_e32 v65, v79, v185
	v_cndmask_b32_e64 v65, v232, v65, s[4:5]
	v_max3_f32 v76, v76, v66, v65
	v_mov_b32_e32 v77, v76
	s_nop 1
	v_permlane32_swap_b32_e32 v76, v77
	v_max_f32_e32 v76, v76, v77
	v_cmp_gt_f32_e32 vcc, v76, v149
	s_cbranch_vccz .LBB0_703
	v_max_f32_e32 v76, v76, v76
	v_max_f32_e32 v77, v149, v149
	v_max_f32_e32 v77, v77, v76
	v_sub_f32_e32 v76, v149, v77
	v_exp_f32_e32 v76, v76
	v_mov_b32_e32 v149, v77
	v_mul_f32_e32 v156, v156, v76
	v_pk_mul_f32 v[62:63], v[62:63], v[76:77] op_sel_hi:[1,0]
	v_pk_mul_f32 v[60:61], v[60:61], v[76:77] op_sel_hi:[1,0]
	v_pk_mul_f32 v[58:59], v[58:59], v[76:77] op_sel_hi:[1,0]
	v_pk_mul_f32 v[56:57], v[56:57], v[76:77] op_sel_hi:[1,0]
	v_pk_mul_f32 v[54:55], v[54:55], v[76:77] op_sel_hi:[1,0]
	v_pk_mul_f32 v[52:53], v[52:53], v[76:77] op_sel_hi:[1,0]
	v_pk_mul_f32 v[50:51], v[50:51], v[76:77] op_sel_hi:[1,0]
	v_pk_mul_f32 v[48:49], v[48:49], v[76:77] op_sel_hi:[1,0]
	v_pk_mul_f32 v[14:15], v[14:15], v[76:77] op_sel_hi:[1,0]
	v_pk_mul_f32 v[12:13], v[12:13], v[76:77] op_sel_hi:[1,0]
	v_pk_mul_f32 v[10:11], v[10:11], v[76:77] op_sel_hi:[1,0]
	v_pk_mul_f32 v[8:9], v[8:9], v[76:77] op_sel_hi:[1,0]
	v_pk_mul_f32 v[6:7], v[6:7], v[76:77] op_sel_hi:[1,0]
	v_pk_mul_f32 v[4:5], v[4:5], v[76:77] op_sel_hi:[1,0]
	v_pk_mul_f32 v[2:3], v[2:3], v[76:77] op_sel_hi:[1,0]
	v_pk_mul_f32 v[0:1], v[0:1], v[76:77] op_sel_hi:[1,0]
	s_branch .LBB0_703

; __device__ __forceinline__ unsigned xb_ld(unsigned* p)              { return __hip_atomic_load(p, __ATOMIC_RELAXED, __HIP_MEMORY_SCOPE_AGENT); }
; __device__ __forceinline__ unsigned xb_add(unsigned* p, unsigned v) { return __hip_atomic_fetch_add(p, v, __ATOMIC_RELAXED, __HIP_MEMORY_SCOPE_AGENT); }
; #define XB_SPIN(cond, bar) do { unsigned _sp = 0; while (cond) { __builtin_amdgcn_s_sleep(1); \
;     if ((++_sp & 255u) == 0u) { if (xb_ld(&(bar)[XB_TMO])) break; if (_sp > XB_SPIN_CAP) { atomicAdd(&(bar)[XB_TMO], 1u); break; } } } } while (0)
; __device__ __forceinline__ unsigned xb_lane() { unsigned l = __builtin_amdgcn_mbcnt_hi(~0u, __builtin_amdgcn_mbcnt_lo(~0u, 0u)); asm volatile("" : "+v"(l)); return l; }
; __device__ __forceinline__ void xcd_barrier(const XcdBarrier& b) {
;     asm volatile("s_waitcnt vmcnt(0)" ::: "memory");
;     __syncthreads();
;     if (b.lead != 0u && xb_lane() == 0u) {
;         unsigned* bar = b.bar;
;         __builtin_amdgcn_s_waitcnt(0);
;         unsigned nloc = b.st[0], nx = b.st[1];
;         if (nloc == 0u) { xcd_barrier_complete(bar, b.x, nloc, nx); b.st[0] = nloc; b.st[1] = nx; }
;         const unsigned old = xb_add(&bar[XB_XSUB(b.x)], 1u);
;         const unsigned gen = old / nloc;
;         if (old + 1u == (gen + 1u) * nloc) {
;             __builtin_amdgcn_fence(__ATOMIC_RELEASE, "agent");
;             asm volatile("s_waitcnt vmcnt(0)" ::: "memory");
;             const unsigned og = xb_add(&bar[XB_TOP], 1u);
;             const unsigned tg = og / nx;
;             if (og + 1u == (tg + 1u) * nx) xb_add(&bar[XB_TOPGEN], 1u);
;             else XB_SPIN(xb_ld(&bar[XB_TOPGEN]) == tg, bar);
;             __builtin_amdgcn_fence(__ATOMIC_ACQUIRE, "agent");
;             xb_add(&bar[XB_XGEN(b.x)], 1u);
;             asm volatile("s_waitcnt vmcnt(0)" ::: "memory");
;         } else {
;             XB_SPIN(xb_ld(&bar[XB_XGEN(b.x)]) == gen, bar);
;             __builtin_amdgcn_fence(__ATOMIC_ACQUIRE, "agent");
;             asm volatile("s_waitcnt vmcnt(0)" ::: "memory");
;         }
;     }
;     __syncthreads();
; }
.LBB0_709:
	s_add_i32 s0, s36, 4
	s_cmp_lt_i32 s0, s51
	s_cselect_b64 s[4:5], -1, 0
	s_and_b64 s[6:7], s[46:47], s[4:5]
	s_andn2_b64 vcc, exec, s[6:7]
	s_cbranch_vccnz .LBB0_796
	v_readlane_b32 s8, v255, 3
	v_readlane_b32 s9, v255, 4
	s_mov_b64 s[6:7], -1
	s_and_b64 vcc, exec, s[8:9]
	s_cbranch_vccz .LBB0_783
	v_readfirstlane_b32 s6, v251
	v_readlane_b32 s1, v255, 2
	s_waitcnt vmcnt(0)
	s_cmp_eq_u32 s6, 0
	s_waitcnt vmcnt(0)
	s_barrier
	s_cbranch_scc1 .LBB0_782
	v_mov_b32_e32 v0, v252
	s_nop 0
	v_cmp_eq_u32_e32 vcc, 0, v0
	s_and_saveexec_b64 s[6:7], vcc
	s_cbranch_execz .LBB0_781
	v_readlane_b32 s8, v255, 26
	s_waitcnt vmcnt(0) expcnt(0) lgkmcnt(0)
	s_nop 0
	v_mov_b32_e32 v0, s8
	ds_read_b32 v2, v0
	v_readlane_b32 s8, v255, 27
	s_waitcnt lgkmcnt(0)
	v_cmp_ne_u32_e32 vcc, 0, v2
	v_mov_b32_e32 v0, s8
	ds_read_b32 v0, v0
	s_cbranch_vccnz .LBB0_745
	v_readlane_b32 s10, v255, 0
	v_readlane_b32 s11, v255, 1
	s_load_dwordx2 s[8:9], s[10:11], 0x4
	s_mov_b32 s15, 1
	s_waitcnt lgkmcnt(0)
	s_mul_i32 s14, s8, s3
	s_mul_i32 s14, s14, s9
	s_branch .LBB0_716
	s_nop 0
	s_nop 0
	s_nop 0
	s_nop 0
